# P3 mid and epilogue ssq loads batched (no per-row vmcnt0 behind atomics), on top of ssq hoist P1/P4 and G1 quota
# speedup vs baseline: 1.0181x; 1.0181x over previous
; __device__ __forceinline__ float ss_get(const ss_t* p) { const ss_t v = *p; return (float)(unsigned)(v >> 32) + (float)(unsigned)v * 2.3283064365386963e-10f; }
;     __device__ __forceinline__ void mid(f32x4 (&acc)[2][2][4][2], const Unit& u, int wr, int wc, int fr, int fq) const {
;         int row0 = u.pm * BM + wr * 64 + fr; asm volatile("" : "+v"(row0));
; #pragma unroll
;         for (int ai = 0; ai < 2; ++ai)
; #pragma unroll
;             for (int m = 0; m < 4; ++m) { const int row = row0 + ai * HALF + m * 16;
;                 const float ra = 1.0f / sqrtf(ss_get(ssa + row) * (1.0f / 1024.f) + 1e-6f), rbi = sqrtf(ss_get(ssb + row) * (1.0f / 1024.f) + 1e-6f); const float ratio = ra * rbi;
; #pragma unroll
;                 for (int bj = 0; bj < 2; ++bj)
; #pragma unroll
;                     for (int n = 0; n < 2; ++n) acc[ai][bj][m][n] = acc[ai][bj][m][n] * ratio; }
.LBB0_927:
	s_cmpk_lg_i32 s46, 0x800
	s_cbranch_scc1 .LBB0_926
	v_mov_b32_e32 v0, v193
	s_flbit_i32_b32 s2, 0
	v_ashrrev_i32_e32 v1, 31, v0
	v_lshlrev_b64 v[0:1], 3, v[0:1]
	v_lshl_add_u64 v[132:133], s[6:7], 0, v[0:1]
	global_load_dwordx2 v[134:135], v[132:133], off
	v_mov_b32_e32 v137, v2
	s_min_u32 s48, s2, 32
	s_sub_i32 s49, 32, s48
	v_lshl_add_u64 v[0:1], s[8:9], 0, v[0:1]
	global_load_dwordx2 v[140:141], v[0:1], off
	global_load_dwordx2 v[142:143], v[132:133], off offset:128
	global_load_dwordx2 v[144:145], v[0:1], off offset:128
	global_load_dwordx2 v[146:147], v[132:133], off offset:256
	global_load_dwordx2 v[148:149], v[0:1], off offset:256
	global_load_dwordx2 v[150:151], v[132:133], off offset:384
	global_load_dwordx2 v[152:153], v[0:1], off offset:384
	global_load_dwordx2 v[154:155], v[132:133], off offset:1024
	global_load_dwordx2 v[212:213], v[0:1], off offset:1024
	global_load_dwordx2 v[214:215], v[132:133], off offset:1152
	global_load_dwordx2 v[216:217], v[0:1], off offset:1152
	global_load_dwordx2 v[218:219], v[132:133], off offset:1280
	global_load_dwordx2 v[220:221], v[132:133], off offset:1408
	global_load_dwordx2 v[222:223], v[0:1], off offset:1280
	global_load_dwordx2 v[224:225], v[0:1], off offset:1408
	s_waitcnt vmcnt(0)
	v_mov_b32_e32 v136, v135
	v_lshlrev_b64 v[136:137], s48, v[136:137]
	v_min_u32_e32 v3, 1, v136
	v_or_b32_e32 v3, v137, v3
	v_cvt_f32_u32_e32 v3, v3
	v_cvt_f32_u32_e32 v134, v134
	v_ldexp_f32 v3, v3, s49
	v_fmac_f32_e32 v3, 0x2f800000, v134
	v_fmamk_f32 v3, v3, 0x3a800000, v205
	v_cmp_gt_f32_e32 vcc, s97, v3
	v_mul_f32_e32 v134, 0x4f800000, v3
	s_nop 0
	v_cndmask_b32_e32 v3, v3, v134, vcc
	v_sqrt_f32_e32 v134, v3
	s_nop 0
	v_add_u32_e32 v135, -1, v134
	v_fma_f32 v136, -v135, v134, v3
	v_cmp_ge_f32_e64 s[2:3], 0, v136
	v_add_u32_e32 v136, 1, v134
	s_nop 0
	v_cndmask_b32_e64 v135, v134, v135, s[2:3]
	v_fma_f32 v134, -v136, v134, v3
	v_cmp_lt_f32_e64 s[2:3], 0, v134
	s_nop 1
	v_cndmask_b32_e64 v134, v135, v136, s[2:3]
	v_mul_f32_e32 v135, 0x37800000, v134
	v_cndmask_b32_e32 v134, v134, v135, vcc
	v_cmp_class_f32_e32 vcc, v3, v206
	s_nop 1
	v_cndmask_b32_e32 v3, v134, v3, vcc
	v_div_scale_f32 v134, s[2:3], v3, v3, 1.0
	v_rcp_f32_e32 v135, v134
	s_nop 0
	v_fma_f32 v136, -v134, v135, 1.0
	v_fmac_f32_e32 v135, v136, v135
	v_div_scale_f32 v136, vcc, 1.0, v3, 1.0
	v_mul_f32_e32 v137, v136, v135
	v_fma_f32 v138, -v134, v137, v136
	v_fmac_f32_e32 v137, v138, v135
	v_fma_f32 v134, -v134, v137, v136
	v_div_fmas_f32 v134, v134, v135, v137
	v_div_fixup_f32 v3, v134, v3, 1.0
	s_nop 1
	v_mov_b32_e32 v134, v140
	v_mov_b32_e32 v135, v141
	v_mov_b32_e32 v137, v2
	v_mov_b32_e32 v136, v135
	v_lshlrev_b64 v[136:137], s48, v[136:137]
	v_min_u32_e32 v135, 1, v136
	v_or_b32_e32 v135, v137, v135
	v_cvt_f32_u32_e32 v135, v135
	v_cvt_f32_u32_e32 v134, v134
	v_ldexp_f32 v135, v135, s49
	v_fmac_f32_e32 v135, 0x2f800000, v134
	v_fmamk_f32 v134, v135, 0x3a800000, v205
	v_cmp_gt_f32_e32 vcc, s97, v134
	v_mul_f32_e32 v135, 0x4f800000, v134
	s_nop 0
	v_cndmask_b32_e32 v134, v134, v135, vcc
	v_sqrt_f32_e32 v135, v134
	s_nop 0
	v_add_u32_e32 v136, -1, v135
	v_fma_f32 v137, -v136, v135, v134
	v_cmp_ge_f32_e64 s[2:3], 0, v137
	v_add_u32_e32 v137, 1, v135
	s_nop 0
	v_cndmask_b32_e64 v136, v135, v136, s[2:3]
	v_fma_f32 v135, -v137, v135, v134
	v_cmp_lt_f32_e64 s[2:3], 0, v135
	s_nop 1
	v_cndmask_b32_e64 v135, v136, v137, s[2:3]
	v_mul_f32_e32 v136, 0x37800000, v135
	v_cndmask_b32_e32 v135, v135, v136, vcc
	v_cmp_class_f32_e32 vcc, v134, v206
	v_mov_b32_e32 v137, v2
	s_nop 0
	v_cndmask_b32_e32 v134, v135, v134, vcc
	v_mul_f32_e32 v134, v3, v134
	v_pk_mul_f32 v[130:131], v[130:131], v[134:135] op_sel_hi:[1,0]
	v_pk_mul_f32 v[128:129], v[128:129], v[134:135] op_sel_hi:[1,0]
	v_pk_mul_f32 v[126:127], v[126:127], v[134:135] op_sel_hi:[1,0]
	v_pk_mul_f32 v[124:125], v[124:125], v[134:135] op_sel_hi:[1,0]
	v_pk_mul_f32 v[122:123], v[122:123], v[134:135] op_sel_hi:[1,0]
	v_pk_mul_f32 v[120:121], v[120:121], v[134:135] op_sel_hi:[1,0]
	v_pk_mul_f32 v[118:119], v[118:119], v[134:135] op_sel_hi:[1,0]
	v_pk_mul_f32 v[116:117], v[116:117], v[134:135] op_sel_hi:[1,0]
	s_nop 1
	v_mov_b32_e32 v134, v142
	v_mov_b32_e32 v135, v143
	v_mov_b32_e32 v136, v135
	v_lshlrev_b64 v[136:137], s48, v[136:137]
	v_min_u32_e32 v3, 1, v136
	v_or_b32_e32 v3, v137, v3
	v_cvt_f32_u32_e32 v3, v3
	v_cvt_f32_u32_e32 v134, v134
	v_ldexp_f32 v3, v3, s49
	v_fmac_f32_e32 v3, 0x2f800000, v134
	v_fmamk_f32 v3, v3, 0x3a800000, v205
	v_cmp_gt_f32_e32 vcc, s97, v3
	v_mul_f32_e32 v134, 0x4f800000, v3
	s_nop 0
	v_cndmask_b32_e32 v3, v3, v134, vcc
	v_sqrt_f32_e32 v134, v3
	s_nop 0
	v_add_u32_e32 v135, -1, v134
	v_fma_f32 v136, -v135, v134, v3
	v_cmp_ge_f32_e64 s[2:3], 0, v136
	v_add_u32_e32 v136, 1, v134
	s_nop 0
	v_cndmask_b32_e64 v135, v134, v135, s[2:3]
	v_fma_f32 v134, -v136, v134, v3
	v_cmp_lt_f32_e64 s[2:3], 0, v134
	s_nop 1
	v_cndmask_b32_e64 v134, v135, v136, s[2:3]
	v_mul_f32_e32 v135, 0x37800000, v134
	v_cndmask_b32_e32 v134, v134, v135, vcc
	v_cmp_class_f32_e32 vcc, v3, v206
	s_nop 1
	v_cndmask_b32_e32 v3, v134, v3, vcc
	v_div_scale_f32 v134, s[2:3], v3, v3, 1.0
	v_rcp_f32_e32 v135, v134
	s_nop 0
	v_fma_f32 v136, -v134, v135, 1.0
	v_fmac_f32_e32 v135, v136, v135
	v_div_scale_f32 v136, vcc, 1.0, v3, 1.0
	v_mul_f32_e32 v137, v136, v135
	v_fma_f32 v138, -v134, v137, v136
	v_fmac_f32_e32 v137, v138, v135
	v_fma_f32 v134, -v134, v137, v136
	v_div_fmas_f32 v134, v134, v135, v137
	v_div_fixup_f32 v3, v134, v3, 1.0
	s_nop 1
	v_mov_b32_e32 v134, v144
	v_mov_b32_e32 v135, v145
	v_mov_b32_e32 v137, v2
	v_mov_b32_e32 v136, v135
	v_lshlrev_b64 v[136:137], s48, v[136:137]
	v_min_u32_e32 v135, 1, v136
; __device__ __forceinline__ float ss_get(const ss_t* p) { const ss_t v = *p; return (float)(unsigned)(v >> 32) + (float)(unsigned)v * 2.3283064365386963e-10f; }
;     __device__ __forceinline__ void mid(f32x4 (&acc)[2][2][4][2], const Unit& u, int wr, int wc, int fr, int fq) const {
;         int row0 = u.pm * BM + wr * 64 + fr; asm volatile("" : "+v"(row0));
; #pragma unroll
;         for (int ai = 0; ai < 2; ++ai)
; #pragma unroll
;             for (int m = 0; m < 4; ++m) { const int row = row0 + ai * HALF + m * 16;
;                 const float ra = 1.0f / sqrtf(ss_get(ssa + row) * (1.0f / 1024.f) + 1e-6f), rbi = sqrtf(ss_get(ssb + row) * (1.0f / 1024.f) + 1e-6f); const float ratio = ra * rbi;
; #pragma unroll
;                 for (int bj = 0; bj < 2; ++bj)
; #pragma unroll
;                     for (int n = 0; n < 2; ++n) acc[ai][bj][m][n] = acc[ai][bj][m][n] * ratio; }
	v_or_b32_e32 v135, v137, v135
	v_cvt_f32_u32_e32 v135, v135
	v_cvt_f32_u32_e32 v134, v134
	v_ldexp_f32 v135, v135, s49
	v_fmac_f32_e32 v135, 0x2f800000, v134
	v_fmamk_f32 v134, v135, 0x3a800000, v205
	v_cmp_gt_f32_e32 vcc, s97, v134
	v_mul_f32_e32 v135, 0x4f800000, v134
	s_nop 0
	v_cndmask_b32_e32 v134, v134, v135, vcc
	v_sqrt_f32_e32 v135, v134
	s_nop 0
	v_add_u32_e32 v136, -1, v135
	v_fma_f32 v137, -v136, v135, v134
	v_cmp_ge_f32_e64 s[2:3], 0, v137
	v_add_u32_e32 v137, 1, v135
	s_nop 0
	v_cndmask_b32_e64 v136, v135, v136, s[2:3]
	v_fma_f32 v135, -v137, v135, v134
	v_cmp_lt_f32_e64 s[2:3], 0, v135
	s_nop 1
	v_cndmask_b32_e64 v135, v136, v137, s[2:3]
	v_mul_f32_e32 v136, 0x37800000, v135
	v_cndmask_b32_e32 v135, v135, v136, vcc
	v_cmp_class_f32_e32 vcc, v134, v206
	v_mov_b32_e32 v137, v2
	s_nop 0
	v_cndmask_b32_e32 v134, v135, v134, vcc
	v_mul_f32_e32 v134, v3, v134
	v_pk_mul_f32 v[114:115], v[114:115], v[134:135] op_sel_hi:[1,0]
	v_pk_mul_f32 v[112:113], v[112:113], v[134:135] op_sel_hi:[1,0]
	v_pk_mul_f32 v[110:111], v[110:111], v[134:135] op_sel_hi:[1,0]
	v_pk_mul_f32 v[108:109], v[108:109], v[134:135] op_sel_hi:[1,0]
	v_pk_mul_f32 v[106:107], v[106:107], v[134:135] op_sel_hi:[1,0]
	v_pk_mul_f32 v[104:105], v[104:105], v[134:135] op_sel_hi:[1,0]
	v_pk_mul_f32 v[102:103], v[102:103], v[134:135] op_sel_hi:[1,0]
	v_pk_mul_f32 v[100:101], v[100:101], v[134:135] op_sel_hi:[1,0]
	s_nop 1
	v_mov_b32_e32 v134, v146
	v_mov_b32_e32 v135, v147
	v_mov_b32_e32 v136, v135
	v_lshlrev_b64 v[136:137], s48, v[136:137]
	v_min_u32_e32 v3, 1, v136
	v_or_b32_e32 v3, v137, v3
	v_cvt_f32_u32_e32 v3, v3
	v_cvt_f32_u32_e32 v134, v134
	v_ldexp_f32 v3, v3, s49
	v_fmac_f32_e32 v3, 0x2f800000, v134
	v_fmamk_f32 v3, v3, 0x3a800000, v205
	v_cmp_gt_f32_e32 vcc, s97, v3
	v_mul_f32_e32 v134, 0x4f800000, v3
	s_nop 0
	v_cndmask_b32_e32 v3, v3, v134, vcc
	v_sqrt_f32_e32 v134, v3
	s_nop 0
	v_add_u32_e32 v135, -1, v134
	v_fma_f32 v136, -v135, v134, v3
	v_cmp_ge_f32_e64 s[2:3], 0, v136
	v_add_u32_e32 v136, 1, v134
	s_nop 0
	v_cndmask_b32_e64 v135, v134, v135, s[2:3]
	v_fma_f32 v134, -v136, v134, v3
	v_cmp_lt_f32_e64 s[2:3], 0, v134
	s_nop 1
	v_cndmask_b32_e64 v134, v135, v136, s[2:3]
	v_mul_f32_e32 v135, 0x37800000, v134
	v_cndmask_b32_e32 v134, v134, v135, vcc
	v_cmp_class_f32_e32 vcc, v3, v206
	s_nop 1
	v_cndmask_b32_e32 v3, v134, v3, vcc
	v_div_scale_f32 v134, s[2:3], v3, v3, 1.0
	v_rcp_f32_e32 v135, v134
	s_nop 0
	v_fma_f32 v136, -v134, v135, 1.0
	v_fmac_f32_e32 v135, v136, v135
	v_div_scale_f32 v136, vcc, 1.0, v3, 1.0
	v_mul_f32_e32 v137, v136, v135
	v_fma_f32 v138, -v134, v137, v136
	v_fmac_f32_e32 v137, v138, v135
	v_fma_f32 v134, -v134, v137, v136
	v_div_fmas_f32 v134, v134, v135, v137
	v_div_fixup_f32 v3, v134, v3, 1.0
	s_nop 1
	v_mov_b32_e32 v134, v148
	v_mov_b32_e32 v135, v149
	v_mov_b32_e32 v137, v2
	v_mov_b32_e32 v136, v135
	v_lshlrev_b64 v[136:137], s48, v[136:137]
	v_min_u32_e32 v135, 1, v136
	v_or_b32_e32 v135, v137, v135
	v_cvt_f32_u32_e32 v135, v135
	v_cvt_f32_u32_e32 v134, v134
	v_ldexp_f32 v135, v135, s49
	v_fmac_f32_e32 v135, 0x2f800000, v134
	v_fmamk_f32 v134, v135, 0x3a800000, v205
	v_cmp_gt_f32_e32 vcc, s97, v134
	v_mul_f32_e32 v135, 0x4f800000, v134
	s_nop 0
	v_cndmask_b32_e32 v134, v134, v135, vcc
	v_sqrt_f32_e32 v135, v134
	s_nop 0
	v_add_u32_e32 v136, -1, v135
	v_fma_f32 v137, -v136, v135, v134
	v_cmp_ge_f32_e64 s[2:3], 0, v137
	v_add_u32_e32 v137, 1, v135
	s_nop 0
	v_cndmask_b32_e64 v136, v135, v136, s[2:3]
	v_fma_f32 v135, -v137, v135, v134
	v_cmp_lt_f32_e64 s[2:3], 0, v135
	s_nop 1
	v_cndmask_b32_e64 v135, v136, v137, s[2:3]
	v_mul_f32_e32 v136, 0x37800000, v135
	v_cndmask_b32_e32 v135, v135, v136, vcc
	v_cmp_class_f32_e32 vcc, v134, v206
	v_mov_b32_e32 v137, v2
	s_nop 0
	v_cndmask_b32_e32 v134, v135, v134, vcc
	v_mul_f32_e32 v134, v3, v134
	v_pk_mul_f32 v[98:99], v[98:99], v[134:135] op_sel_hi:[1,0]
	v_pk_mul_f32 v[96:97], v[96:97], v[134:135] op_sel_hi:[1,0]
	v_pk_mul_f32 v[94:95], v[94:95], v[134:135] op_sel_hi:[1,0]
	v_pk_mul_f32 v[92:93], v[92:93], v[134:135] op_sel_hi:[1,0]
	v_pk_mul_f32 v[90:91], v[90:91], v[134:135] op_sel_hi:[1,0]
	v_pk_mul_f32 v[88:89], v[88:89], v[134:135] op_sel_hi:[1,0]
	v_pk_mul_f32 v[86:87], v[86:87], v[134:135] op_sel_hi:[1,0]
	v_pk_mul_f32 v[84:85], v[84:85], v[134:135] op_sel_hi:[1,0]
	s_nop 1
	v_mov_b32_e32 v134, v150
	v_mov_b32_e32 v135, v151
	v_mov_b32_e32 v136, v135
	v_lshlrev_b64 v[136:137], s48, v[136:137]
	v_min_u32_e32 v3, 1, v136
	v_or_b32_e32 v3, v137, v3
	v_cvt_f32_u32_e32 v3, v3
	v_cvt_f32_u32_e32 v134, v134
	v_ldexp_f32 v3, v3, s49
	v_fmac_f32_e32 v3, 0x2f800000, v134
	v_fmamk_f32 v3, v3, 0x3a800000, v205
	v_cmp_gt_f32_e32 vcc, s97, v3
	v_mul_f32_e32 v134, 0x4f800000, v3
	s_nop 0
	v_cndmask_b32_e32 v3, v3, v134, vcc
	v_sqrt_f32_e32 v134, v3
	s_nop 0
	v_add_u32_e32 v135, -1, v134
	v_fma_f32 v136, -v135, v134, v3
	v_cmp_ge_f32_e64 s[2:3], 0, v136
	v_add_u32_e32 v136, 1, v134
	s_nop 0
	v_cndmask_b32_e64 v135, v134, v135, s[2:3]
	v_fma_f32 v134, -v136, v134, v3
	v_cmp_lt_f32_e64 s[2:3], 0, v134
	s_nop 1
	v_cndmask_b32_e64 v134, v135, v136, s[2:3]
	v_mul_f32_e32 v135, 0x37800000, v134
	v_cndmask_b32_e32 v134, v134, v135, vcc
	v_cmp_class_f32_e32 vcc, v3, v206
	s_nop 1
	v_cndmask_b32_e32 v3, v134, v3, vcc
	v_div_scale_f32 v134, s[2:3], v3, v3, 1.0
	v_rcp_f32_e32 v135, v134
	s_nop 0
	v_fma_f32 v136, -v134, v135, 1.0
	v_fmac_f32_e32 v135, v136, v135
	v_div_scale_f32 v136, vcc, 1.0, v3, 1.0
	v_mul_f32_e32 v137, v136, v135
	v_fma_f32 v138, -v134, v137, v136
	v_fmac_f32_e32 v137, v138, v135
	v_fma_f32 v134, -v134, v137, v136
	v_div_fmas_f32 v134, v134, v135, v137
	v_div_fixup_f32 v3, v134, v3, 1.0
	s_nop 1
; __device__ __forceinline__ float ss_get(const ss_t* p) { const ss_t v = *p; return (float)(unsigned)(v >> 32) + (float)(unsigned)v * 2.3283064365386963e-10f; }
;     __device__ __forceinline__ void mid(f32x4 (&acc)[2][2][4][2], const Unit& u, int wr, int wc, int fr, int fq) const {
;         int row0 = u.pm * BM + wr * 64 + fr; asm volatile("" : "+v"(row0));
; #pragma unroll
;         for (int ai = 0; ai < 2; ++ai)
; #pragma unroll
;             for (int m = 0; m < 4; ++m) { const int row = row0 + ai * HALF + m * 16;
;                 const float ra = 1.0f / sqrtf(ss_get(ssa + row) * (1.0f / 1024.f) + 1e-6f), rbi = sqrtf(ss_get(ssb + row) * (1.0f / 1024.f) + 1e-6f); const float ratio = ra * rbi;
; #pragma unroll
;                 for (int bj = 0; bj < 2; ++bj)
; #pragma unroll
;                     for (int n = 0; n < 2; ++n) acc[ai][bj][m][n] = acc[ai][bj][m][n] * ratio; }
	v_mov_b32_e32 v134, v152
	v_mov_b32_e32 v135, v153
	v_mov_b32_e32 v137, v2
	v_mov_b32_e32 v136, v135
	v_lshlrev_b64 v[136:137], s48, v[136:137]
	v_min_u32_e32 v135, 1, v136
	v_or_b32_e32 v135, v137, v135
	v_cvt_f32_u32_e32 v135, v135
	v_cvt_f32_u32_e32 v134, v134
	v_ldexp_f32 v135, v135, s49
	v_fmac_f32_e32 v135, 0x2f800000, v134
	v_fmamk_f32 v134, v135, 0x3a800000, v205
	v_cmp_gt_f32_e32 vcc, s97, v134
	v_mul_f32_e32 v135, 0x4f800000, v134
	s_nop 0
	v_cndmask_b32_e32 v134, v134, v135, vcc
	v_sqrt_f32_e32 v135, v134
	s_nop 0
	v_add_u32_e32 v136, -1, v135
	v_fma_f32 v137, -v136, v135, v134
	v_cmp_ge_f32_e64 s[2:3], 0, v137
	v_add_u32_e32 v137, 1, v135
	s_nop 0
	v_cndmask_b32_e64 v136, v135, v136, s[2:3]
	v_fma_f32 v135, -v137, v135, v134
	v_cmp_lt_f32_e64 s[2:3], 0, v135
	s_nop 1
	v_cndmask_b32_e64 v135, v136, v137, s[2:3]
	v_mul_f32_e32 v136, 0x37800000, v135
	v_cndmask_b32_e32 v135, v135, v136, vcc
	v_cmp_class_f32_e32 vcc, v134, v206
	v_mov_b32_e32 v137, v2
	s_nop 0
	v_cndmask_b32_e32 v134, v135, v134, vcc
	v_mul_f32_e32 v134, v3, v134
	v_pk_mul_f32 v[82:83], v[82:83], v[134:135] op_sel_hi:[1,0]
	v_pk_mul_f32 v[80:81], v[80:81], v[134:135] op_sel_hi:[1,0]
	v_pk_mul_f32 v[78:79], v[78:79], v[134:135] op_sel_hi:[1,0]
	v_pk_mul_f32 v[76:77], v[76:77], v[134:135] op_sel_hi:[1,0]
	v_pk_mul_f32 v[74:75], v[74:75], v[134:135] op_sel_hi:[1,0]
	v_pk_mul_f32 v[72:73], v[72:73], v[134:135] op_sel_hi:[1,0]
	v_pk_mul_f32 v[70:71], v[70:71], v[134:135] op_sel_hi:[1,0]
	v_pk_mul_f32 v[68:69], v[68:69], v[134:135] op_sel_hi:[1,0]
	s_nop 1
	v_mov_b32_e32 v134, v154
	v_mov_b32_e32 v135, v155
	v_mov_b32_e32 v136, v135
	v_lshlrev_b64 v[136:137], s48, v[136:137]
	v_min_u32_e32 v3, 1, v136
	v_or_b32_e32 v3, v137, v3
	v_cvt_f32_u32_e32 v3, v3
	v_cvt_f32_u32_e32 v134, v134
	v_ldexp_f32 v3, v3, s49
	v_fmac_f32_e32 v3, 0x2f800000, v134
	v_fmamk_f32 v3, v3, 0x3a800000, v205
	v_cmp_gt_f32_e32 vcc, s97, v3
	v_mul_f32_e32 v134, 0x4f800000, v3
	s_nop 0
	v_cndmask_b32_e32 v3, v3, v134, vcc
	v_sqrt_f32_e32 v134, v3
	s_nop 0
	v_add_u32_e32 v135, -1, v134
	v_fma_f32 v136, -v135, v134, v3
	v_cmp_ge_f32_e64 s[2:3], 0, v136
	v_add_u32_e32 v136, 1, v134
	s_nop 0
	v_cndmask_b32_e64 v135, v134, v135, s[2:3]
	v_fma_f32 v134, -v136, v134, v3
	v_cmp_lt_f32_e64 s[2:3], 0, v134
	s_nop 1
	v_cndmask_b32_e64 v134, v135, v136, s[2:3]
	v_mul_f32_e32 v135, 0x37800000, v134
	v_cndmask_b32_e32 v134, v134, v135, vcc
	v_cmp_class_f32_e32 vcc, v3, v206
	s_nop 1
	v_cndmask_b32_e32 v3, v134, v3, vcc
	v_div_scale_f32 v134, s[2:3], v3, v3, 1.0
	v_rcp_f32_e32 v135, v134
	s_nop 0
	v_fma_f32 v136, -v134, v135, 1.0
	v_fmac_f32_e32 v135, v136, v135
	v_div_scale_f32 v136, vcc, 1.0, v3, 1.0
	v_mul_f32_e32 v137, v136, v135
	v_fma_f32 v138, -v134, v137, v136
	v_fmac_f32_e32 v137, v138, v135
	v_fma_f32 v134, -v134, v137, v136
	v_div_fmas_f32 v134, v134, v135, v137
	v_div_fixup_f32 v3, v134, v3, 1.0
	s_nop 1
	v_mov_b32_e32 v134, v212
	v_mov_b32_e32 v135, v213
	v_mov_b32_e32 v137, v2
	v_mov_b32_e32 v136, v135
	v_lshlrev_b64 v[136:137], s48, v[136:137]
	v_min_u32_e32 v135, 1, v136
	v_or_b32_e32 v135, v137, v135
	v_cvt_f32_u32_e32 v135, v135
	v_cvt_f32_u32_e32 v134, v134
	v_ldexp_f32 v135, v135, s49
	v_fmac_f32_e32 v135, 0x2f800000, v134
	v_fmamk_f32 v134, v135, 0x3a800000, v205
	v_cmp_gt_f32_e32 vcc, s97, v134
	v_mul_f32_e32 v135, 0x4f800000, v134
	s_nop 0
	v_cndmask_b32_e32 v134, v134, v135, vcc
	v_sqrt_f32_e32 v135, v134
	s_nop 0
	v_add_u32_e32 v136, -1, v135
	v_fma_f32 v137, -v136, v135, v134
	v_cmp_ge_f32_e64 s[2:3], 0, v137
	v_add_u32_e32 v137, 1, v135
	s_nop 0
	v_cndmask_b32_e64 v136, v135, v136, s[2:3]
	v_fma_f32 v135, -v137, v135, v134
	v_cmp_lt_f32_e64 s[2:3], 0, v135
	s_nop 1
	v_cndmask_b32_e64 v135, v136, v137, s[2:3]
	v_mul_f32_e32 v136, 0x37800000, v135
	v_cndmask_b32_e32 v135, v135, v136, vcc
	v_cmp_class_f32_e32 vcc, v134, v206
	v_mov_b32_e32 v137, v2
	s_nop 0
	v_cndmask_b32_e32 v134, v135, v134, vcc
	v_mul_f32_e32 v134, v3, v134
	v_pk_mul_f32 v[66:67], v[66:67], v[134:135] op_sel_hi:[1,0]
	v_pk_mul_f32 v[64:65], v[64:65], v[134:135] op_sel_hi:[1,0]
	v_pk_mul_f32 v[62:63], v[62:63], v[134:135] op_sel_hi:[1,0]
	v_pk_mul_f32 v[60:61], v[60:61], v[134:135] op_sel_hi:[1,0]
	v_pk_mul_f32 v[58:59], v[58:59], v[134:135] op_sel_hi:[1,0]
	v_pk_mul_f32 v[56:57], v[56:57], v[134:135] op_sel_hi:[1,0]
	v_pk_mul_f32 v[54:55], v[54:55], v[134:135] op_sel_hi:[1,0]
	v_pk_mul_f32 v[52:53], v[52:53], v[134:135] op_sel_hi:[1,0]
	s_nop 1
	v_mov_b32_e32 v134, v214
	v_mov_b32_e32 v135, v215
	v_mov_b32_e32 v136, v135
	v_lshlrev_b64 v[136:137], s48, v[136:137]
	v_min_u32_e32 v3, 1, v136
	v_or_b32_e32 v3, v137, v3
	v_cvt_f32_u32_e32 v3, v3
	v_cvt_f32_u32_e32 v134, v134
	v_ldexp_f32 v3, v3, s49
	v_fmac_f32_e32 v3, 0x2f800000, v134
	v_fmamk_f32 v3, v3, 0x3a800000, v205
	v_cmp_gt_f32_e32 vcc, s97, v3
	v_mul_f32_e32 v134, 0x4f800000, v3
	s_nop 0
	v_cndmask_b32_e32 v3, v3, v134, vcc
	v_sqrt_f32_e32 v134, v3
	s_nop 0
	v_add_u32_e32 v135, -1, v134
	v_fma_f32 v136, -v135, v134, v3
	v_cmp_ge_f32_e64 s[2:3], 0, v136
	v_add_u32_e32 v136, 1, v134
	s_nop 0
	v_cndmask_b32_e64 v135, v134, v135, s[2:3]
	v_fma_f32 v134, -v136, v134, v3
	v_cmp_lt_f32_e64 s[2:3], 0, v134
	s_nop 1
	v_cndmask_b32_e64 v134, v135, v136, s[2:3]
	v_mul_f32_e32 v135, 0x37800000, v134
	v_cndmask_b32_e32 v134, v134, v135, vcc
	v_cmp_class_f32_e32 vcc, v3, v206
	s_nop 1
	v_cndmask_b32_e32 v3, v134, v3, vcc
	v_div_scale_f32 v134, s[2:3], v3, v3, 1.0
	v_rcp_f32_e32 v135, v134
	s_nop 0
	v_fma_f32 v136, -v134, v135, 1.0
	v_fmac_f32_e32 v135, v136, v135
	v_div_scale_f32 v136, vcc, 1.0, v3, 1.0
	v_mul_f32_e32 v137, v136, v135
	v_fma_f32 v138, -v134, v137, v136
; __device__ __forceinline__ float ss_get(const ss_t* p) { const ss_t v = *p; return (float)(unsigned)(v >> 32) + (float)(unsigned)v * 2.3283064365386963e-10f; }
;     __device__ __forceinline__ void mid(f32x4 (&acc)[2][2][4][2], const Unit& u, int wr, int wc, int fr, int fq) const {
;         int row0 = u.pm * BM + wr * 64 + fr; asm volatile("" : "+v"(row0));
; #pragma unroll
;         for (int ai = 0; ai < 2; ++ai)
; #pragma unroll
;             for (int m = 0; m < 4; ++m) { const int row = row0 + ai * HALF + m * 16;
;                 const float ra = 1.0f / sqrtf(ss_get(ssa + row) * (1.0f / 1024.f) + 1e-6f), rbi = sqrtf(ss_get(ssb + row) * (1.0f / 1024.f) + 1e-6f); const float ratio = ra * rbi;
; #pragma unroll
;                 for (int bj = 0; bj < 2; ++bj)
; #pragma unroll
;                     for (int n = 0; n < 2; ++n) acc[ai][bj][m][n] = acc[ai][bj][m][n] * ratio; }
	v_fmac_f32_e32 v137, v138, v135
	v_fma_f32 v134, -v134, v137, v136
	v_div_fmas_f32 v134, v134, v135, v137
	v_div_fixup_f32 v3, v134, v3, 1.0
	s_nop 1
	v_mov_b32_e32 v134, v216
	v_mov_b32_e32 v135, v217
	v_mov_b32_e32 v137, v2
	v_mov_b32_e32 v136, v135
	v_lshlrev_b64 v[136:137], s48, v[136:137]
	v_min_u32_e32 v135, 1, v136
	v_or_b32_e32 v135, v137, v135
	v_cvt_f32_u32_e32 v135, v135
	v_cvt_f32_u32_e32 v134, v134
	v_ldexp_f32 v135, v135, s49
	v_fmac_f32_e32 v135, 0x2f800000, v134
	v_fmamk_f32 v134, v135, 0x3a800000, v205
	v_cmp_gt_f32_e32 vcc, s97, v134
	v_mul_f32_e32 v135, 0x4f800000, v134
	s_nop 0
	v_cndmask_b32_e32 v134, v134, v135, vcc
	v_sqrt_f32_e32 v135, v134
	s_nop 0
	v_add_u32_e32 v136, -1, v135
	v_fma_f32 v137, -v136, v135, v134
	v_cmp_ge_f32_e64 s[2:3], 0, v137
	v_add_u32_e32 v137, 1, v135
	s_nop 0
	v_cndmask_b32_e64 v136, v135, v136, s[2:3]
	v_fma_f32 v135, -v137, v135, v134
	v_cmp_lt_f32_e64 s[2:3], 0, v135
	s_nop 1
	v_cndmask_b32_e64 v135, v136, v137, s[2:3]
	v_mul_f32_e32 v136, 0x37800000, v135
	v_cndmask_b32_e32 v135, v135, v136, vcc
	v_cmp_class_f32_e32 vcc, v134, v206
	v_mov_b32_e32 v137, v2
	s_nop 0
	v_cndmask_b32_e32 v134, v135, v134, vcc
	v_mul_f32_e32 v134, v3, v134
	v_pk_mul_f32 v[50:51], v[50:51], v[134:135] op_sel_hi:[1,0]
	v_pk_mul_f32 v[48:49], v[48:49], v[134:135] op_sel_hi:[1,0]
	v_pk_mul_f32 v[46:47], v[46:47], v[134:135] op_sel_hi:[1,0]
	v_pk_mul_f32 v[44:45], v[44:45], v[134:135] op_sel_hi:[1,0]
	v_pk_mul_f32 v[42:43], v[42:43], v[134:135] op_sel_hi:[1,0]
	v_pk_mul_f32 v[40:41], v[40:41], v[134:135] op_sel_hi:[1,0]
	v_pk_mul_f32 v[38:39], v[38:39], v[134:135] op_sel_hi:[1,0]
	v_pk_mul_f32 v[36:37], v[36:37], v[134:135] op_sel_hi:[1,0]
	s_nop 1
	v_mov_b32_e32 v134, v218
	v_mov_b32_e32 v135, v219
	v_mov_b32_e32 v136, v135
	v_lshlrev_b64 v[136:137], s48, v[136:137]
	v_min_u32_e32 v3, 1, v136
	v_or_b32_e32 v3, v137, v3
	v_cvt_f32_u32_e32 v3, v3
	v_cvt_f32_u32_e32 v134, v134
	s_nop 1
	v_mov_b32_e32 v132, v220
	v_mov_b32_e32 v133, v221
	v_ldexp_f32 v3, v3, s49
	v_fmac_f32_e32 v3, 0x2f800000, v134
	v_fmamk_f32 v3, v3, 0x3a800000, v205
	v_cmp_gt_f32_e32 vcc, s97, v3
	v_mul_f32_e32 v134, 0x4f800000, v3
	v_cvt_f32_u32_e32 v132, v132
	v_cndmask_b32_e32 v3, v3, v134, vcc
	v_sqrt_f32_e32 v134, v3
	s_nop 0
	v_add_u32_e32 v135, -1, v134
	v_fma_f32 v136, -v135, v134, v3
	v_cmp_ge_f32_e64 s[2:3], 0, v136
	v_add_u32_e32 v136, 1, v134
	s_nop 0
	v_cndmask_b32_e64 v135, v134, v135, s[2:3]
	v_fma_f32 v134, -v136, v134, v3
	v_cmp_lt_f32_e64 s[2:3], 0, v134
	s_nop 1
	v_cndmask_b32_e64 v134, v135, v136, s[2:3]
	v_mul_f32_e32 v135, 0x37800000, v134
	v_cndmask_b32_e32 v134, v134, v135, vcc
	v_cmp_class_f32_e32 vcc, v3, v206
	s_nop 1
	v_cndmask_b32_e32 v3, v134, v3, vcc
	v_div_scale_f32 v134, s[2:3], v3, v3, 1.0
	v_rcp_f32_e32 v135, v134
	s_nop 0
	v_fma_f32 v136, -v134, v135, 1.0
	v_fmac_f32_e32 v135, v136, v135
	v_div_scale_f32 v136, vcc, 1.0, v3, 1.0
	v_mul_f32_e32 v137, v136, v135
	v_fma_f32 v138, -v134, v137, v136
	v_fmac_f32_e32 v137, v138, v135
	v_fma_f32 v134, -v134, v137, v136
	v_div_fmas_f32 v134, v134, v135, v137
	v_div_fixup_f32 v3, v134, v3, 1.0
	s_nop 1
	v_mov_b32_e32 v134, v222
	v_mov_b32_e32 v135, v223
	v_mov_b32_e32 v137, v2
	s_nop 1
	v_mov_b32_e32 v0, v224
	v_mov_b32_e32 v1, v225
	v_mov_b32_e32 v136, v135
	v_lshlrev_b64 v[136:137], s48, v[136:137]
	v_min_u32_e32 v135, 1, v136
	v_or_b32_e32 v135, v137, v135
	v_cvt_f32_u32_e32 v135, v135
	v_cvt_f32_u32_e32 v134, v134
	v_cvt_f32_u32_e32 v0, v0
	v_ldexp_f32 v135, v135, s49
	v_fmac_f32_e32 v135, 0x2f800000, v134
	v_fmamk_f32 v134, v135, 0x3a800000, v205
	v_cmp_gt_f32_e32 vcc, s97, v134
	v_mul_f32_e32 v135, 0x4f800000, v134
	s_nop 0
; __device__ __forceinline__ float ss_get(const ss_t* p) { const ss_t v = *p; return (float)(unsigned)(v >> 32) + (float)(unsigned)v * 2.3283064365386963e-10f; }
;     __device__ __forceinline__ void mid(f32x4 (&acc)[2][2][4][2], const Unit& u, int wr, int wc, int fr, int fq) const {
;         int row0 = u.pm * BM + wr * 64 + fr; asm volatile("" : "+v"(row0));
; #pragma unroll
;         for (int ai = 0; ai < 2; ++ai)
; #pragma unroll
;             for (int m = 0; m < 4; ++m) { const int row = row0 + ai * HALF + m * 16;
;                 const float ra = 1.0f / sqrtf(ss_get(ssa + row) * (1.0f / 1024.f) + 1e-6f), rbi = sqrtf(ss_get(ssb + row) * (1.0f / 1024.f) + 1e-6f); const float ratio = ra * rbi;
; #pragma unroll
;                 for (int bj = 0; bj < 2; ++bj)
; #pragma unroll
;                     for (int n = 0; n < 2; ++n) acc[ai][bj][m][n] = acc[ai][bj][m][n] * ratio; }
	v_cndmask_b32_e32 v134, v134, v135, vcc
	v_sqrt_f32_e32 v135, v134
	s_nop 0
	v_add_u32_e32 v136, -1, v135
	v_fma_f32 v137, -v136, v135, v134
	v_cmp_ge_f32_e64 s[2:3], 0, v137
	v_add_u32_e32 v137, 1, v135
	s_nop 0
	v_cndmask_b32_e64 v136, v135, v136, s[2:3]
	v_fma_f32 v135, -v137, v135, v134
	v_cmp_lt_f32_e64 s[2:3], 0, v135
	s_nop 1
	v_cndmask_b32_e64 v135, v136, v137, s[2:3]
	v_mul_f32_e32 v136, 0x37800000, v135
	v_cndmask_b32_e32 v135, v135, v136, vcc
	v_cmp_class_f32_e32 vcc, v134, v206
	s_nop 1
	v_cndmask_b32_e32 v134, v135, v134, vcc
	v_mul_f32_e32 v134, v3, v134
	v_pk_mul_f32 v[34:35], v[34:35], v[134:135] op_sel_hi:[1,0]
	v_pk_mul_f32 v[32:33], v[32:33], v[134:135] op_sel_hi:[1,0]
	v_pk_mul_f32 v[30:31], v[30:31], v[134:135] op_sel_hi:[1,0]
	v_pk_mul_f32 v[28:29], v[28:29], v[134:135] op_sel_hi:[1,0]
	v_pk_mul_f32 v[26:27], v[26:27], v[134:135] op_sel_hi:[1,0]
	v_pk_mul_f32 v[24:25], v[24:25], v[134:135] op_sel_hi:[1,0]
	v_pk_mul_f32 v[22:23], v[22:23], v[134:135] op_sel_hi:[1,0]
	v_pk_mul_f32 v[20:21], v[20:21], v[134:135] op_sel_hi:[1,0]
	v_mov_b32_e32 v134, v133
	v_mov_b32_e32 v135, v2
	v_lshlrev_b64 v[134:135], s48, v[134:135]
	v_min_u32_e32 v3, 1, v134
	v_or_b32_e32 v3, v135, v3
	v_cvt_f32_u32_e32 v3, v3
	v_ldexp_f32 v3, v3, s49
	v_fmac_f32_e32 v3, 0x2f800000, v132
	v_fmamk_f32 v3, v3, 0x3a800000, v205
	v_cmp_gt_f32_e32 vcc, s97, v3
	v_mul_f32_e32 v132, 0x4f800000, v3
	s_nop 0
	v_cndmask_b32_e32 v3, v3, v132, vcc
	v_sqrt_f32_e32 v132, v3
	s_nop 0
	v_add_u32_e32 v133, -1, v132
	v_fma_f32 v134, -v133, v132, v3
	v_cmp_ge_f32_e64 s[2:3], 0, v134
	v_add_u32_e32 v134, 1, v132
	s_nop 0
	v_cndmask_b32_e64 v133, v132, v133, s[2:3]
	v_fma_f32 v132, -v134, v132, v3
	v_cmp_lt_f32_e64 s[2:3], 0, v132
	s_nop 1
	v_cndmask_b32_e64 v132, v133, v134, s[2:3]
	v_mul_f32_e32 v133, 0x37800000, v132
	v_cndmask_b32_e32 v132, v132, v133, vcc
	v_cmp_class_f32_e32 vcc, v3, v206
	s_nop 1
	v_cndmask_b32_e32 v3, v132, v3, vcc
	v_div_scale_f32 v132, s[2:3], v3, v3, 1.0
	v_rcp_f32_e32 v133, v132
	s_nop 0
	v_fma_f32 v134, -v132, v133, 1.0
	v_fmac_f32_e32 v133, v134, v133
	v_div_scale_f32 v134, vcc, 1.0, v3, 1.0
	v_mul_f32_e32 v135, v134, v133
	v_fma_f32 v136, -v132, v135, v134
	v_fmac_f32_e32 v135, v136, v133
	v_fma_f32 v132, -v132, v135, v134
	v_div_fmas_f32 v132, v132, v133, v135
	v_div_fixup_f32 v3, v132, v3, 1.0
	v_mov_b32_e32 v132, v1
	v_mov_b32_e32 v133, v2
	v_lshlrev_b64 v[132:133], s48, v[132:133]
	v_min_u32_e32 v1, 1, v132
	v_or_b32_e32 v1, v133, v1
	v_cvt_f32_u32_e32 v1, v1
	v_ldexp_f32 v1, v1, s49
	v_fmac_f32_e32 v1, 0x2f800000, v0
	v_fmamk_f32 v0, v1, 0x3a800000, v205
	v_cmp_gt_f32_e32 vcc, s97, v0
	v_mul_f32_e32 v1, 0x4f800000, v0
	s_nop 0
	v_cndmask_b32_e32 v0, v0, v1, vcc
	v_sqrt_f32_e32 v1, v0
	s_nop 0
	v_add_u32_e32 v132, -1, v1
	v_fma_f32 v133, -v132, v1, v0
	v_cmp_ge_f32_e64 s[2:3], 0, v133
	v_add_u32_e32 v133, 1, v1
	s_nop 0
	v_cndmask_b32_e64 v132, v1, v132, s[2:3]
	v_fma_f32 v1, -v133, v1, v0
	v_cmp_lt_f32_e64 s[2:3], 0, v1
	s_nop 1
	v_cndmask_b32_e64 v1, v132, v133, s[2:3]
	v_mul_f32_e32 v132, 0x37800000, v1
	v_cndmask_b32_e32 v1, v1, v132, vcc
	v_cmp_class_f32_e32 vcc, v0, v206
	s_nop 1
	v_cndmask_b32_e32 v0, v1, v0, vcc
	v_mul_f32_e32 v0, v3, v0
	v_pk_mul_f32 v[18:19], v[18:19], v[0:1] op_sel_hi:[1,0]
	v_pk_mul_f32 v[16:17], v[16:17], v[0:1] op_sel_hi:[1,0]
	v_pk_mul_f32 v[14:15], v[14:15], v[0:1] op_sel_hi:[1,0]
	v_pk_mul_f32 v[12:13], v[12:13], v[0:1] op_sel_hi:[1,0]
	v_pk_mul_f32 v[10:11], v[10:11], v[0:1] op_sel_hi:[1,0]
	v_pk_mul_f32 v[8:9], v[8:9], v[0:1] op_sel_hi:[1,0]
	v_pk_mul_f32 v[6:7], v[6:7], v[0:1] op_sel_hi:[1,0]
	v_pk_mul_f32 v[4:5], v[4:5], v[0:1] op_sel_hi:[1,0]
	s_branch .LBB0_926

; __device__ __forceinline__ void ss_add(ss_t* p, float sq) { const float fl = floorf(sq); const unsigned hi = (unsigned)fl, lo = (unsigned)((sq - fl) * 4294967296.0f); atomicAdd(p, ((ss_t)hi << 32) | (ss_t)lo); }
;     __device__ __forceinline__ void operator()(const f32x4 (&acc)[2][2][4][2], const Unit& u, int wr, int wc, int fr, int fq) const {
;         int row0 = u.pm * BM + wr * 64 + fr; asm volatile("" : "+v"(row0));     const int col0 = u.pn * BM + wc * 32 + 8 * fq;
; #pragma unroll
;         for (int ai = 0; ai < 2; ++ai) {
;             u32x4 res[4][2];
; #pragma unroll
;             for (int m = 0; m < 4; ++m) { const bf16_t* rowp = XB + (size_t)(row0 + ai * HALF + m * 16) * ldc + col0;
; #pragma unroll
;                 for (int bj = 0; bj < 2; ++bj) res[m][bj] = *(const u32x4*)(rowp + bj * HALF); }
;             asm volatile("" ::: "memory");
; #pragma unroll
;             for (int m = 0; m < 4; ++m) { const int row = row0 + ai * HALF + m * 16; const size_t off = (size_t)row * ldc + col0;
;                 float rs = 1.0f; if (KS) rs = 1.0f / sqrtf(ss_get(ssb + row) * (1.0f / 1024.f) + 1e-6f);
;                 float sq = 0.f;
; #pragma unroll
;                 for (int bj = 0; bj < 2; ++bj) { const u32x4 r = res[m][bj];
;                     const f32x4 x0 = (f32x4){__uint_as_float(r.x << 16), __uint_as_float(r.x & 0xffff0000u), __uint_as_float(r.y << 16), __uint_as_float(r.y & 0xffff0000u)};
;                     const f32x4 x1 = (f32x4){__uint_as_float(r.z << 16), __uint_as_float(r.z & 0xffff0000u), __uint_as_float(r.w << 16), __uint_as_float(r.w & 0xffff0000u)};
;                     const f32x4 v0 = x0 + acc[ai][bj][m][0] * rs, v1 = x1 + acc[ai][bj][m][1] * rs;
;                     if (OUT) { *(f32x4*)(OUT + off + bj * HALF) = v0; *(f32x4*)(OUT + off + bj * HALF + 4) = v1; }
;                     else { sq += ((v0[0] * v0[0] + v0[1] * v0[1]) + (v0[2] * v0[2] + v0[3] * v0[3])) + ((v1[0] * v1[0] + v1[1] * v1[1]) + (v1[2] * v1[2] + v1[3] * v1[3]));
;                         u32x4 w; w.x = pkbf(v0[0], v0[1]); w.y = pkbf(v0[2], v0[3]); w.z = pkbf(v1[0], v1[1]); w.w = pkbf(v1[2], v1[3]); *(u32x4*)(XB + off + bj * HALF) = w; } }
;                 if (!OUT) { sq += __shfl_xor(sq, 16); sq += __shfl_xor(sq, 32); if (fq == 0) ss_add(ssq_out + row, sq); } }
.LBB0_931:
	v_lshl_or_b32 v0, s60, 8, v194
	v_mov_b32_e32 v182, v193
	v_ashrrev_i32_e32 v1, 31, v0
	v_lshlrev_b64 v[212:213], 1, v[0:1]
	v_ashrrev_i32_e32 v183, 31, v182
	v_lshl_add_u64 v[184:185], s[64:65], 0, v[212:213]
	v_lshlrev_b64 v[214:215], 12, v[182:183]
	v_add_u32_e32 v190, 16, v182
	v_lshl_add_u64 v[132:133], v[184:185], 0, v[214:215]
	v_ashrrev_i32_e32 v191, 31, v190
	global_load_dwordx4 v[196:199], v[132:133], off
	global_load_dwordx4 v[200:203], v[132:133], off offset:256
	v_lshlrev_b64 v[132:133], 12, v[190:191]
	v_add_u32_e32 v188, 32, v182
	v_lshl_add_u64 v[132:133], v[184:185], 0, v[132:133]
	v_ashrrev_i32_e32 v189, 31, v188
	global_load_dwordx4 v[152:155], v[132:133], off
	global_load_dwordx4 v[148:151], v[132:133], off offset:256
	v_lshlrev_b64 v[132:133], 12, v[188:189]
	v_add_u32_e32 v186, 48, v182
	v_lshl_add_u64 v[132:133], v[184:185], 0, v[132:133]
	v_ashrrev_i32_e32 v187, 31, v186
	global_load_dwordx4 v[144:147], v[132:133], off
	global_load_dwordx4 v[140:143], v[132:133], off offset:256
	v_lshlrev_b64 v[132:133], 12, v[186:187]
	v_lshl_add_u64 v[132:133], v[184:185], 0, v[132:133]
	global_load_dwordx4 v[136:139], v[132:133], off
	s_nop 0
	global_load_dwordx4 v[132:135], v[132:133], off offset:256
	v_lshl_add_u64 v[180:181], v[182:183], 3, s[8:9]
	global_load_dwordx2 v[216:217], v[180:181], off
	global_load_dwordx2 v[222:223], v[180:181], off offset:128
	global_load_dwordx2 v[224:225], v[180:181], off offset:256
	global_load_dwordx2 v[226:227], v[180:181], off offset:384
	global_load_dwordx2 v[228:229], v[180:181], off offset:1024
	global_load_dwordx2 v[230:231], v[180:181], off offset:1152
	global_load_dwordx2 v[232:233], v[180:181], off offset:1280
	global_load_dwordx2 v[234:235], v[180:181], off offset:1408
	s_flbit_i32_b32 s2, 0
	v_mov_b32_e32 v219, v2
	s_min_u32 s43, s2, 32
	s_sub_i32 s46, 32, s43
	s_waitcnt vmcnt(0)
	v_and_b32_e32 v221, 0xffff0000, v198
	v_mov_b32_e32 v218, v217
	v_lshlrev_b64 v[218:219], s43, v[218:219]
	v_min_u32_e32 v3, 1, v218
	v_or_b32_e32 v3, v219, v3
	v_cvt_f32_u32_e32 v3, v3
	v_cvt_f32_u32_e32 v216, v216
	v_ldexp_f32 v3, v3, s46
	v_fmac_f32_e32 v3, 0x2f800000, v216
	v_fmamk_f32 v3, v3, 0x3a800000, v205
	v_cmp_gt_f32_e32 vcc, s97, v3
	v_mul_f32_e32 v216, 0x4f800000, v3
	s_nop 0
	v_cndmask_b32_e32 v3, v3, v216, vcc
	v_sqrt_f32_e32 v216, v3
	s_nop 0
	v_add_u32_e32 v217, -1, v216
	v_fma_f32 v218, -v217, v216, v3
	v_cmp_ge_f32_e64 s[2:3], 0, v218
	v_add_u32_e32 v218, 1, v216
	s_nop 0
	v_cndmask_b32_e64 v217, v216, v217, s[2:3]
	v_fma_f32 v216, -v218, v216, v3
	v_cmp_lt_f32_e64 s[2:3], 0, v216
	s_nop 1
	v_cndmask_b32_e64 v216, v217, v218, s[2:3]
	v_mul_f32_e32 v217, 0x37800000, v216
	v_cndmask_b32_e32 v216, v216, v217, vcc
	v_cmp_class_f32_e32 vcc, v3, v206
	s_nop 1
	v_cndmask_b32_e32 v3, v216, v3, vcc
	v_div_scale_f32 v216, s[2:3], v3, v3, 1.0
	v_rcp_f32_e32 v217, v216
	s_nop 0
	v_fma_f32 v218, -v216, v217, 1.0
	v_fmac_f32_e32 v217, v218, v217
	v_div_scale_f32 v218, vcc, 1.0, v3, 1.0
	v_mul_f32_e32 v219, v218, v217
	v_fma_f32 v220, -v216, v219, v218
	v_fmac_f32_e32 v219, v220, v217
	v_fma_f32 v216, -v216, v219, v218
	v_div_fmas_f32 v216, v216, v217, v219
	v_div_fixup_f32 v216, v216, v3, 1.0
	v_lshlrev_b32_e32 v218, 16, v196
	v_and_b32_e32 v219, 0xffff0000, v196
	v_lshlrev_b32_e32 v196, 16, v197
	v_and_b32_e32 v197, 0xffff0000, v197
	v_lshlrev_b32_e32 v220, 16, v198
	v_lshlrev_b32_e32 v198, 16, v199
	v_and_b32_e32 v199, 0xffff0000, v199
	v_pk_fma_f32 v[130:131], v[130:131], v[216:217], v[196:197] op_sel_hi:[1,0,1]
	v_pk_fma_f32 v[128:129], v[128:129], v[216:217], v[218:219] op_sel_hi:[1,0,1]
	v_pk_fma_f32 v[196:197], v[126:127], v[216:217], v[198:199] op_sel_hi:[1,0,1]
	v_pk_fma_f32 v[126:127], v[124:125], v[216:217], v[220:221] op_sel_hi:[1,0,1]
	v_mul_f32_e32 v3, v129, v129
	v_mul_f32_e32 v124, v131, v131
	v_fmac_f32_e32 v3, v128, v128
	v_fmac_f32_e32 v124, v130, v130
	v_add_f32_e32 v3, v3, v124
	v_mul_f32_e32 v124, v127, v127
	v_mul_f32_e32 v125, v197, v197
	v_fmac_f32_e32 v124, v126, v126
	v_fmac_f32_e32 v125, v196, v196
	v_add_f32_e32 v124, v124, v125
	v_add_f32_e32 v3, v3, v124
	v_cvt_pk_bf16_f32 v124, v128, v129
	v_lshl_add_u64 v[128:129], s[64:65], 0, v[214:215]
	v_cvt_pk_bf16_f32 v125, v130, v131
	v_cvt_pk_bf16_f32 v126, v126, v127
	v_cvt_pk_bf16_f32 v127, v196, v197
	v_lshl_add_u64 v[128:129], v[128:129], 0, v[212:213]
	global_store_dwordx4 v[128:129], v[124:127], off
	v_lshlrev_b32_e32 v130, 16, v202
	v_and_b32_e32 v131, 0xffff0000, v202
	v_lshlrev_b32_e32 v124, 16, v200
	v_and_b32_e32 v125, 0xffff0000, v200
	v_lshlrev_b32_e32 v126, 16, v201
	v_and_b32_e32 v127, 0xffff0000, v201
	v_pk_fma_f32 v[122:123], v[122:123], v[216:217], v[126:127] op_sel_hi:[1,0,1]
	v_pk_fma_f32 v[120:121], v[120:121], v[216:217], v[124:125] op_sel_hi:[1,0,1]
	v_lshlrev_b32_e32 v196, 16, v203
	v_and_b32_e32 v197, 0xffff0000, v203
	v_pk_fma_f32 v[126:127], v[116:117], v[216:217], v[130:131] op_sel_hi:[1,0,1]
	v_mul_f32_e32 v116, v121, v121
	v_mul_f32_e32 v117, v123, v123
	v_pk_fma_f32 v[124:125], v[118:119], v[216:217], v[196:197] op_sel_hi:[1,0,1]
	v_fmac_f32_e32 v116, v120, v120
	v_fmac_f32_e32 v117, v122, v122
	v_add_f32_e32 v116, v116, v117
	v_mul_f32_e32 v117, v127, v127
	v_mul_f32_e32 v118, v125, v125
	v_fmac_f32_e32 v117, v126, v126
	v_fmac_f32_e32 v118, v124, v124
	v_add_f32_e32 v117, v117, v118
	v_add_f32_e32 v116, v116, v117
	v_and_b32_e32 v117, 64, v208
	v_add_f32_e32 v116, v3, v116
	v_xor_b32_e32 v3, 16, v208
	v_add_u32_e32 v117, 64, v117
	v_cmp_lt_i32_e32 vcc, v3, v117
	v_cvt_pk_bf16_f32 v118, v120, v121
	v_cvt_pk_bf16_f32 v119, v122, v123
	v_cndmask_b32_e32 v3, v208, v3, vcc
	v_cvt_pk_bf16_f32 v120, v126, v127
	v_cvt_pk_bf16_f32 v121, v124, v125
	v_lshlrev_b32_e32 v3, 2, v3
	global_store_dwordx4 v[128:129], v[118:121], off offset:256
	ds_bpermute_b32 v118, v3, v116
	s_waitcnt lgkmcnt(0)
	v_add_f32_e32 v116, v116, v118
	v_xor_b32_e32 v118, 32, v208
	v_cmp_lt_i32_e32 vcc, v118, v117
	s_nop 1
	v_cndmask_b32_e32 v117, v208, v118, vcc
	v_lshlrev_b32_e32 v117, 2, v117
	ds_bpermute_b32 v118, v117, v116
	s_and_saveexec_b64 s[2:3], s[40:41]
	s_cbranch_execz .LBB0_933
	s_waitcnt lgkmcnt(0)
	v_add_f32_e32 v116, v116, v118
	v_floor_f32_e32 v118, v116
	v_sub_f32_e32 v116, v116, v118
	v_mul_f32_e32 v116, 0x4f800000, v116
	v_cvt_u32_f32_e32 v119, v118
	v_cvt_u32_f32_e32 v118, v116
	v_lshl_add_u64 v[120:121], v[182:183], 3, s[4:5]
	global_atomic_add_x2 v[120:121], v[118:119], off
; __device__ __forceinline__ void ss_add(ss_t* p, float sq) { const float fl = floorf(sq); const unsigned hi = (unsigned)fl, lo = (unsigned)((sq - fl) * 4294967296.0f); atomicAdd(p, ((ss_t)hi << 32) | (ss_t)lo); }
; __device__ __forceinline__ float ss_get(const ss_t* p) { const ss_t v = *p; return (float)(unsigned)(v >> 32) + (float)(unsigned)v * 2.3283064365386963e-10f; }
; __device__ __forceinline__ unsigned pkbf(float lo, float hi) { typedef float f2_t __attribute__((ext_vector_type(2))); typedef __bf16 b2_t __attribute__((ext_vector_type(2))); f2_t v = {lo, hi}; b2_t b = __builtin_convertvector(v, b2_t); return __builtin_bit_cast(unsigned, b); }
;     __device__ __forceinline__ void operator()(const f32x4 (&acc)[2][2][4][2], const Unit& u, int wr, int wc, int fr, int fq) const {
;     ...
;             for (int m = 0; m < 4; ++m) { const int row = row0 + ai * HALF + m * 16; const size_t off = (size_t)row * ldc + col0;
;                 float rs = 1.0f; if (KS) rs = 1.0f / sqrtf(ss_get(ssb + row) * (1.0f / 1024.f) + 1e-6f);
;                 float sq = 0.f;
; #pragma unroll
;                 for (int bj = 0; bj < 2; ++bj) { const u32x4 r = res[m][bj];
;                     const f32x4 x0 = (f32x4){__uint_as_float(r.x << 16), __uint_as_float(r.x & 0xffff0000u), __uint_as_float(r.y << 16), __uint_as_float(r.y & 0xffff0000u)};
;                     const f32x4 x1 = (f32x4){__uint_as_float(r.z << 16), __uint_as_float(r.z & 0xffff0000u), __uint_as_float(r.w << 16), __uint_as_float(r.w & 0xffff0000u)};
;                     const f32x4 v0 = x0 + acc[ai][bj][m][0] * rs, v1 = x1 + acc[ai][bj][m][1] * rs;
;                     if (OUT) { *(f32x4*)(OUT + off + bj * HALF) = v0; *(f32x4*)(OUT + off + bj * HALF + 4) = v1; }
;                     else { sq += ((v0[0] * v0[0] + v0[1] * v0[1]) + (v0[2] * v0[2] + v0[3] * v0[3])) + ((v1[0] * v1[0] + v1[1] * v1[1]) + (v1[2] * v1[2] + v1[3] * v1[3]));
;                         u32x4 w; w.x = pkbf(v0[0], v0[1]); w.y = pkbf(v0[2], v0[3]); w.z = pkbf(v1[0], v1[1]); w.w = pkbf(v1[2], v1[3]); *(u32x4*)(XB + off + bj * HALF) = w; } }
;                 if (!OUT) { sq += __shfl_xor(sq, 16); sq += __shfl_xor(sq, 32); if (fq == 0) ss_add(ssq_out + row, sq); } }
.LBB0_933:
	s_or_b64 exec, exec, s[2:3]
	s_nop 1
	v_mov_b32_e32 v120, v222
	v_mov_b32_e32 v121, v223
	v_mov_b32_e32 v123, v2
	v_lshlrev_b32_e32 v126, 16, v155
	v_and_b32_e32 v127, 0xffff0000, v155
	v_and_b32_e32 v125, 0xffff0000, v154
	s_waitcnt lgkmcnt(0)
	v_lshlrev_b64 v[118:119], 11, v[190:191]
	v_mov_b32_e32 v122, v121
	v_lshlrev_b64 v[122:123], s43, v[122:123]
	v_min_u32_e32 v116, 1, v122
	v_or_b32_e32 v116, v123, v116
	v_cvt_f32_u32_e32 v116, v116
	v_cvt_f32_u32_e32 v120, v120
	v_ldexp_f32 v116, v116, s46
	v_fmac_f32_e32 v116, 0x2f800000, v120
	v_fmamk_f32 v116, v116, 0x3a800000, v205
	v_cmp_gt_f32_e32 vcc, s97, v116
	v_mul_f32_e32 v120, 0x4f800000, v116
	s_nop 0
	v_cndmask_b32_e32 v116, v116, v120, vcc
	v_sqrt_f32_e32 v120, v116
	s_nop 0
	v_add_u32_e32 v121, -1, v120
	v_fma_f32 v122, -v121, v120, v116
	v_cmp_ge_f32_e64 s[2:3], 0, v122
	v_add_u32_e32 v122, 1, v120
	s_nop 0
	v_cndmask_b32_e64 v121, v120, v121, s[2:3]
	v_fma_f32 v120, -v122, v120, v116
	v_cmp_lt_f32_e64 s[2:3], 0, v120
	s_nop 1
	v_cndmask_b32_e64 v120, v121, v122, s[2:3]
	v_mul_f32_e32 v121, 0x37800000, v120
	v_cndmask_b32_e32 v120, v120, v121, vcc
	v_cmp_class_f32_e32 vcc, v116, v206
	s_nop 1
	v_cndmask_b32_e32 v116, v120, v116, vcc
	v_div_scale_f32 v120, s[2:3], v116, v116, 1.0
	v_rcp_f32_e32 v121, v120
	s_nop 0
	v_fma_f32 v122, -v120, v121, 1.0
	v_fmac_f32_e32 v121, v122, v121
	v_div_scale_f32 v122, vcc, 1.0, v116, 1.0
	v_mul_f32_e32 v123, v122, v121
	v_fma_f32 v124, -v120, v123, v122
	v_fmac_f32_e32 v123, v124, v121
	v_fma_f32 v120, -v120, v123, v122
	v_div_fmas_f32 v120, v120, v121, v123
	v_div_fixup_f32 v116, v120, v116, 1.0
	v_lshlrev_b32_e32 v120, 16, v152
	v_and_b32_e32 v121, 0xffff0000, v152
	v_lshlrev_b32_e32 v122, 16, v153
	v_and_b32_e32 v123, 0xffff0000, v153
	v_pk_fma_f32 v[114:115], v[114:115], v[116:117], v[122:123] op_sel_hi:[1,0,1]
	v_pk_fma_f32 v[112:113], v[112:113], v[116:117], v[120:121] op_sel_hi:[1,0,1]
	v_lshlrev_b32_e32 v124, 16, v154
	v_pk_fma_f32 v[120:121], v[110:111], v[116:117], v[126:127] op_sel_hi:[1,0,1]
	v_mul_f32_e32 v110, v113, v113
	v_mul_f32_e32 v111, v115, v115
	v_pk_fma_f32 v[108:109], v[108:109], v[116:117], v[124:125] op_sel_hi:[1,0,1]
	v_fmac_f32_e32 v110, v112, v112
	v_fmac_f32_e32 v111, v114, v114
	v_add_f32_e32 v110, v110, v111
	v_mul_f32_e32 v111, v109, v109
	v_mul_f32_e32 v122, v121, v121
	v_fmac_f32_e32 v111, v108, v108
	v_fmac_f32_e32 v122, v120, v120
	v_add_f32_e32 v111, v111, v122
	v_add_f32_e32 v122, v110, v111
	v_cvt_pk_bf16_f32 v110, v112, v113
	v_cvt_pk_bf16_f32 v112, v108, v109
	v_lshl_add_u64 v[108:109], v[118:119], 1, s[64:65]
	v_cvt_pk_bf16_f32 v111, v114, v115
	v_cvt_pk_bf16_f32 v113, v120, v121
	v_lshl_add_u64 v[108:109], v[0:1], 1, v[108:109]
	global_store_dwordx4 v[108:109], v[110:113], off
	v_lshlrev_b32_e32 v114, 16, v150
	v_and_b32_e32 v115, 0xffff0000, v150
	v_lshlrev_b32_e32 v110, 16, v148
	v_and_b32_e32 v111, 0xffff0000, v148
	v_lshlrev_b32_e32 v112, 16, v149
	v_and_b32_e32 v113, 0xffff0000, v149
	v_lshlrev_b32_e32 v118, 16, v151
	v_and_b32_e32 v119, 0xffff0000, v151
	v_pk_fma_f32 v[106:107], v[106:107], v[116:117], v[112:113] op_sel_hi:[1,0,1]
	v_pk_fma_f32 v[104:105], v[104:105], v[116:117], v[110:111] op_sel_hi:[1,0,1]
	v_pk_fma_f32 v[110:111], v[102:103], v[116:117], v[118:119] op_sel_hi:[1,0,1]
	v_pk_fma_f32 v[102:103], v[100:101], v[116:117], v[114:115] op_sel_hi:[1,0,1]
	v_mul_f32_e32 v100, v105, v105
	v_mul_f32_e32 v101, v107, v107
	v_fmac_f32_e32 v100, v104, v104
	v_fmac_f32_e32 v101, v106, v106
	v_add_f32_e32 v100, v100, v101
	v_mul_f32_e32 v101, v103, v103
	v_mul_f32_e32 v112, v111, v111
	v_fmac_f32_e32 v101, v102, v102
	v_fmac_f32_e32 v112, v110, v110
	v_add_f32_e32 v101, v101, v112
	v_add_f32_e32 v100, v100, v101
	v_add_f32_e32 v112, v122, v100
	v_cvt_pk_bf16_f32 v100, v104, v105
	v_cvt_pk_bf16_f32 v101, v106, v107
	v_cvt_pk_bf16_f32 v102, v102, v103
	v_cvt_pk_bf16_f32 v103, v110, v111
	global_store_dwordx4 v[108:109], v[100:103], off offset:256
	ds_bpermute_b32 v100, v3, v112
	s_waitcnt lgkmcnt(0)
	v_add_f32_e32 v100, v112, v100
	ds_bpermute_b32 v101, v117, v100
	s_and_saveexec_b64 s[2:3], s[40:41]
	s_cbranch_execz .LBB0_935
	s_waitcnt lgkmcnt(0)
	v_add_f32_e32 v102, v100, v101
	v_floor_f32_e32 v104, v102
	v_sub_f32_e32 v102, v102, v104
	v_mul_f32_e32 v102, 0x4f800000, v102
	v_cvt_u32_f32_e32 v103, v104
	v_cvt_u32_f32_e32 v102, v102
	v_lshl_add_u64 v[100:101], v[190:191], 3, s[4:5]
	global_atomic_add_x2 v[100:101], v[102:103], off
; __device__ __forceinline__ void ss_add(ss_t* p, float sq) { const float fl = floorf(sq); const unsigned hi = (unsigned)fl, lo = (unsigned)((sq - fl) * 4294967296.0f); atomicAdd(p, ((ss_t)hi << 32) | (ss_t)lo); }
; __device__ __forceinline__ float ss_get(const ss_t* p) { const ss_t v = *p; return (float)(unsigned)(v >> 32) + (float)(unsigned)v * 2.3283064365386963e-10f; }
; __device__ __forceinline__ unsigned pkbf(float lo, float hi) { typedef float f2_t __attribute__((ext_vector_type(2))); typedef __bf16 b2_t __attribute__((ext_vector_type(2))); f2_t v = {lo, hi}; b2_t b = __builtin_convertvector(v, b2_t); return __builtin_bit_cast(unsigned, b); }
;     __device__ __forceinline__ void operator()(const f32x4 (&acc)[2][2][4][2], const Unit& u, int wr, int wc, int fr, int fq) const {
;     ...
;             for (int m = 0; m < 4; ++m) { const int row = row0 + ai * HALF + m * 16; const size_t off = (size_t)row * ldc + col0;
;                 float rs = 1.0f; if (KS) rs = 1.0f / sqrtf(ss_get(ssb + row) * (1.0f / 1024.f) + 1e-6f);
;                 float sq = 0.f;
; #pragma unroll
;                 for (int bj = 0; bj < 2; ++bj) { const u32x4 r = res[m][bj];
;                     const f32x4 x0 = (f32x4){__uint_as_float(r.x << 16), __uint_as_float(r.x & 0xffff0000u), __uint_as_float(r.y << 16), __uint_as_float(r.y & 0xffff0000u)};
;                     const f32x4 x1 = (f32x4){__uint_as_float(r.z << 16), __uint_as_float(r.z & 0xffff0000u), __uint_as_float(r.w << 16), __uint_as_float(r.w & 0xffff0000u)};
;                     const f32x4 v0 = x0 + acc[ai][bj][m][0] * rs, v1 = x1 + acc[ai][bj][m][1] * rs;
;                     if (OUT) { *(f32x4*)(OUT + off + bj * HALF) = v0; *(f32x4*)(OUT + off + bj * HALF + 4) = v1; }
;                     else { sq += ((v0[0] * v0[0] + v0[1] * v0[1]) + (v0[2] * v0[2] + v0[3] * v0[3])) + ((v1[0] * v1[0] + v1[1] * v1[1]) + (v1[2] * v1[2] + v1[3] * v1[3]));
;                         u32x4 w; w.x = pkbf(v0[0], v0[1]); w.y = pkbf(v0[2], v0[3]); w.z = pkbf(v1[0], v1[1]); w.w = pkbf(v1[2], v1[3]); *(u32x4*)(XB + off + bj * HALF) = w; } }
;                 if (!OUT) { sq += __shfl_xor(sq, 16); sq += __shfl_xor(sq, 32); if (fq == 0) ss_add(ssq_out + row, sq); } }
.LBB0_935:
	s_or_b64 exec, exec, s[2:3]
	s_waitcnt lgkmcnt(0)
	s_nop 1
	v_mov_b32_e32 v100, v224
	v_mov_b32_e32 v101, v225
	v_mov_b32_e32 v105, v2
	v_lshlrev_b32_e32 v110, 16, v147
	v_and_b32_e32 v111, 0xffff0000, v147
	v_lshlrev_b32_e32 v108, 16, v146
	v_and_b32_e32 v109, 0xffff0000, v146
	v_lshlrev_b64 v[102:103], 11, v[188:189]
	v_mov_b32_e32 v104, v101
	v_lshlrev_b64 v[104:105], s43, v[104:105]
	v_min_u32_e32 v101, 1, v104
	v_or_b32_e32 v101, v105, v101
	v_cvt_f32_u32_e32 v101, v101
	v_cvt_f32_u32_e32 v100, v100
	v_ldexp_f32 v101, v101, s46
	v_fmac_f32_e32 v101, 0x2f800000, v100
	v_fmamk_f32 v100, v101, 0x3a800000, v205
	v_cmp_gt_f32_e32 vcc, s97, v100
	v_mul_f32_e32 v101, 0x4f800000, v100
	s_nop 0
	v_cndmask_b32_e32 v100, v100, v101, vcc
	v_sqrt_f32_e32 v101, v100
	s_nop 0
	v_add_u32_e32 v104, -1, v101
	v_fma_f32 v105, -v104, v101, v100
	v_cmp_ge_f32_e64 s[2:3], 0, v105
	v_add_u32_e32 v105, 1, v101
	s_nop 0
	v_cndmask_b32_e64 v104, v101, v104, s[2:3]
	v_fma_f32 v101, -v105, v101, v100
	v_cmp_lt_f32_e64 s[2:3], 0, v101
	s_nop 1
	v_cndmask_b32_e64 v101, v104, v105, s[2:3]
	v_mul_f32_e32 v104, 0x37800000, v101
	v_cndmask_b32_e32 v101, v101, v104, vcc
	v_cmp_class_f32_e32 vcc, v100, v206
	s_nop 1
	v_cndmask_b32_e32 v100, v101, v100, vcc
	v_div_scale_f32 v101, s[2:3], v100, v100, 1.0
	v_rcp_f32_e32 v104, v101
	s_nop 0
	v_fma_f32 v105, -v101, v104, 1.0
	v_fmac_f32_e32 v104, v105, v104
	v_div_scale_f32 v105, vcc, 1.0, v100, 1.0
	v_mul_f32_e32 v106, v105, v104
	v_fma_f32 v107, -v101, v106, v105
	v_fmac_f32_e32 v106, v107, v104
	v_fma_f32 v101, -v101, v106, v105
	v_div_fmas_f32 v101, v101, v104, v106
	v_div_fixup_f32 v100, v101, v100, 1.0
	v_lshlrev_b32_e32 v104, 16, v144
	v_and_b32_e32 v105, 0xffff0000, v144
	v_lshlrev_b32_e32 v106, 16, v145
	v_and_b32_e32 v107, 0xffff0000, v145
	v_pk_fma_f32 v[98:99], v[98:99], v[100:101], v[106:107] op_sel_hi:[1,0,1]
	v_pk_fma_f32 v[96:97], v[96:97], v[100:101], v[104:105] op_sel_hi:[1,0,1]
	v_pk_fma_f32 v[104:105], v[94:95], v[100:101], v[110:111] op_sel_hi:[1,0,1]
	v_mul_f32_e32 v94, v97, v97
	v_mul_f32_e32 v95, v99, v99
	v_pk_fma_f32 v[92:93], v[92:93], v[100:101], v[108:109] op_sel_hi:[1,0,1]
	v_fmac_f32_e32 v94, v96, v96
	v_fmac_f32_e32 v95, v98, v98
	v_add_f32_e32 v94, v94, v95
	v_mul_f32_e32 v95, v93, v93
	v_mul_f32_e32 v101, v105, v105
	v_fmac_f32_e32 v95, v92, v92
	v_fmac_f32_e32 v101, v104, v104
	v_add_f32_e32 v95, v95, v101
	v_add_f32_e32 v101, v94, v95
	v_cvt_pk_bf16_f32 v94, v96, v97
	v_cvt_pk_bf16_f32 v96, v92, v93
	v_lshl_add_u64 v[92:93], v[102:103], 1, s[64:65]
	v_cvt_pk_bf16_f32 v95, v98, v99
	v_cvt_pk_bf16_f32 v97, v104, v105
	v_lshl_add_u64 v[92:93], v[0:1], 1, v[92:93]
	global_store_dwordx4 v[92:93], v[94:97], off
	v_lshlrev_b32_e32 v98, 16, v142
	v_and_b32_e32 v99, 0xffff0000, v142
	v_lshlrev_b32_e32 v94, 16, v140
	v_and_b32_e32 v95, 0xffff0000, v140
	v_lshlrev_b32_e32 v96, 16, v141
	v_and_b32_e32 v97, 0xffff0000, v141
	v_lshlrev_b32_e32 v102, 16, v143
	v_and_b32_e32 v103, 0xffff0000, v143
	v_pk_fma_f32 v[90:91], v[90:91], v[100:101], v[96:97] op_sel_hi:[1,0,1]
	v_pk_fma_f32 v[88:89], v[88:89], v[100:101], v[94:95] op_sel_hi:[1,0,1]
	v_pk_fma_f32 v[94:95], v[86:87], v[100:101], v[102:103] op_sel_hi:[1,0,1]
	v_pk_fma_f32 v[86:87], v[84:85], v[100:101], v[98:99] op_sel_hi:[1,0,1]
	v_mul_f32_e32 v84, v89, v89
	v_mul_f32_e32 v85, v91, v91
	v_fmac_f32_e32 v84, v88, v88
	v_fmac_f32_e32 v85, v90, v90
	v_add_f32_e32 v84, v84, v85
	v_mul_f32_e32 v85, v87, v87
	v_mul_f32_e32 v96, v95, v95
	v_fmac_f32_e32 v85, v86, v86
	v_fmac_f32_e32 v96, v94, v94
	v_add_f32_e32 v85, v85, v96
	v_add_f32_e32 v84, v84, v85
	v_add_f32_e32 v96, v101, v84
	v_cvt_pk_bf16_f32 v84, v88, v89
	v_cvt_pk_bf16_f32 v85, v90, v91
	v_cvt_pk_bf16_f32 v86, v86, v87
	v_cvt_pk_bf16_f32 v87, v94, v95
	global_store_dwordx4 v[92:93], v[84:87], off offset:256
	ds_bpermute_b32 v84, v3, v96
	s_waitcnt lgkmcnt(0)
	v_add_f32_e32 v84, v96, v84
	ds_bpermute_b32 v85, v117, v84
	s_and_saveexec_b64 s[2:3], s[40:41]
	s_cbranch_execz .LBB0_937
	s_waitcnt lgkmcnt(0)
	v_add_f32_e32 v86, v84, v85
	v_floor_f32_e32 v88, v86
	v_sub_f32_e32 v86, v86, v88
	v_mul_f32_e32 v86, 0x4f800000, v86
	v_cvt_u32_f32_e32 v87, v88
	v_cvt_u32_f32_e32 v86, v86
	v_lshl_add_u64 v[84:85], v[188:189], 3, s[4:5]
	global_atomic_add_x2 v[84:85], v[86:87], off
; __device__ __forceinline__ void ss_add(ss_t* p, float sq) { const float fl = floorf(sq); const unsigned hi = (unsigned)fl, lo = (unsigned)((sq - fl) * 4294967296.0f); atomicAdd(p, ((ss_t)hi << 32) | (ss_t)lo); }
; __device__ __forceinline__ float ss_get(const ss_t* p) { const ss_t v = *p; return (float)(unsigned)(v >> 32) + (float)(unsigned)v * 2.3283064365386963e-10f; }
;     __device__ __forceinline__ void operator()(const f32x4 (&acc)[2][2][4][2], const Unit& u, int wr, int wc, int fr, int fq) const {
;     ...
;         for (int ai = 0; ai < 2; ++ai) {
;             u32x4 res[4][2];
; #pragma unroll
;             for (int m = 0; m < 4; ++m) { const bf16_t* rowp = XB + (size_t)(row0 + ai * HALF + m * 16) * ldc + col0;
; #pragma unroll
;                 for (int bj = 0; bj < 2; ++bj) res[m][bj] = *(const u32x4*)(rowp + bj * HALF); }
;     ...
;             for (int m = 0; m < 4; ++m) { const int row = row0 + ai * HALF + m * 16; const size_t off = (size_t)row * ldc + col0;
;                 float rs = 1.0f; if (KS) rs = 1.0f / sqrtf(ss_get(ssb + row) * (1.0f / 1024.f) + 1e-6f);
;                 float sq = 0.f;
; #pragma unroll
;                 for (int bj = 0; bj < 2; ++bj) { const u32x4 r = res[m][bj];
;                     const f32x4 x0 = (f32x4){__uint_as_float(r.x << 16), __uint_as_float(r.x & 0xffff0000u), __uint_as_float(r.y << 16), __uint_as_float(r.y & 0xffff0000u)};
;                     const f32x4 x1 = (f32x4){__uint_as_float(r.z << 16), __uint_as_float(r.z & 0xffff0000u), __uint_as_float(r.w << 16), __uint_as_float(r.w & 0xffff0000u)};
;                     const f32x4 v0 = x0 + acc[ai][bj][m][0] * rs, v1 = x1 + acc[ai][bj][m][1] * rs;
;                     if (OUT) { *(f32x4*)(OUT + off + bj * HALF) = v0; *(f32x4*)(OUT + off + bj * HALF + 4) = v1; }
;                     else { sq += ((v0[0] * v0[0] + v0[1] * v0[1]) + (v0[2] * v0[2] + v0[3] * v0[3])) + ((v1[0] * v1[0] + v1[1] * v1[1]) + (v1[2] * v1[2] + v1[3] * v1[3]));
;                         u32x4 w; w.x = pkbf(v0[0], v0[1]); w.y = pkbf(v0[2], v0[3]); w.z = pkbf(v1[0], v1[1]); w.w = pkbf(v1[2], v1[3]); *(u32x4*)(XB + off + bj * HALF) = w; } }
;                 if (!OUT) { sq += __shfl_xor(sq, 16); sq += __shfl_xor(sq, 32); if (fq == 0) ss_add(ssq_out + row, sq); } }
.LBB0_937:
	s_or_b64 exec, exec, s[2:3]
	s_waitcnt lgkmcnt(0)
	s_nop 1
	v_mov_b32_e32 v84, v226
	v_mov_b32_e32 v85, v227
	v_mov_b32_e32 v89, v2
	v_lshlrev_b32_e32 v94, 16, v139
	v_and_b32_e32 v95, 0xffff0000, v139
	v_lshlrev_b32_e32 v92, 16, v138
	v_and_b32_e32 v93, 0xffff0000, v138
	v_lshlrev_b64 v[86:87], 11, v[186:187]
	v_mov_b32_e32 v88, v85
	v_lshlrev_b64 v[88:89], s43, v[88:89]
	v_min_u32_e32 v85, 1, v88
	v_or_b32_e32 v85, v89, v85
	v_cvt_f32_u32_e32 v85, v85
	v_cvt_f32_u32_e32 v84, v84
	v_ldexp_f32 v85, v85, s46
	v_fmac_f32_e32 v85, 0x2f800000, v84
	v_fmamk_f32 v84, v85, 0x3a800000, v205
	v_cmp_gt_f32_e32 vcc, s97, v84
	v_mul_f32_e32 v85, 0x4f800000, v84
	s_nop 0
	v_cndmask_b32_e32 v84, v84, v85, vcc
	v_sqrt_f32_e32 v85, v84
	s_nop 0
	v_add_u32_e32 v88, -1, v85
	v_fma_f32 v89, -v88, v85, v84
	v_cmp_ge_f32_e64 s[2:3], 0, v89
	v_add_u32_e32 v89, 1, v85
	s_nop 0
	v_cndmask_b32_e64 v88, v85, v88, s[2:3]
	v_fma_f32 v85, -v89, v85, v84
	v_cmp_lt_f32_e64 s[2:3], 0, v85
	s_nop 1
	v_cndmask_b32_e64 v85, v88, v89, s[2:3]
	v_mul_f32_e32 v88, 0x37800000, v85
	v_cndmask_b32_e32 v85, v85, v88, vcc
	v_cmp_class_f32_e32 vcc, v84, v206
	s_nop 1
	v_cndmask_b32_e32 v84, v85, v84, vcc
	v_div_scale_f32 v85, s[2:3], v84, v84, 1.0
	v_rcp_f32_e32 v88, v85
	s_nop 0
	v_fma_f32 v89, -v85, v88, 1.0
	v_fmac_f32_e32 v88, v89, v88
	v_div_scale_f32 v89, vcc, 1.0, v84, 1.0
	v_mul_f32_e32 v90, v89, v88
	v_fma_f32 v91, -v85, v90, v89
	v_fmac_f32_e32 v90, v91, v88
	v_fma_f32 v85, -v85, v90, v89
	v_div_fmas_f32 v85, v85, v88, v90
	v_div_fixup_f32 v84, v85, v84, 1.0
	v_lshlrev_b32_e32 v88, 16, v136
	v_and_b32_e32 v89, 0xffff0000, v136
	v_lshlrev_b32_e32 v90, 16, v137
	v_and_b32_e32 v91, 0xffff0000, v137
	v_pk_fma_f32 v[82:83], v[82:83], v[84:85], v[90:91] op_sel_hi:[1,0,1]
	v_pk_fma_f32 v[80:81], v[80:81], v[84:85], v[88:89] op_sel_hi:[1,0,1]
	v_pk_fma_f32 v[88:89], v[78:79], v[84:85], v[94:95] op_sel_hi:[1,0,1]
	v_mul_f32_e32 v78, v81, v81
	v_mul_f32_e32 v79, v83, v83
	v_pk_fma_f32 v[76:77], v[76:77], v[84:85], v[92:93] op_sel_hi:[1,0,1]
	v_fmac_f32_e32 v78, v80, v80
	v_fmac_f32_e32 v79, v82, v82
	v_add_f32_e32 v78, v78, v79
	v_mul_f32_e32 v79, v77, v77
	v_mul_f32_e32 v85, v89, v89
	v_fmac_f32_e32 v79, v76, v76
	v_fmac_f32_e32 v85, v88, v88
	v_add_f32_e32 v79, v79, v85
	v_add_f32_e32 v85, v78, v79
	v_cvt_pk_bf16_f32 v78, v80, v81
	v_cvt_pk_bf16_f32 v80, v76, v77
	v_lshl_add_u64 v[76:77], v[86:87], 1, s[64:65]
	v_cvt_pk_bf16_f32 v79, v82, v83
	v_cvt_pk_bf16_f32 v81, v88, v89
	v_lshl_add_u64 v[76:77], v[0:1], 1, v[76:77]
	global_store_dwordx4 v[76:77], v[78:81], off
	v_lshlrev_b32_e32 v82, 16, v134
	v_and_b32_e32 v83, 0xffff0000, v134
	v_lshlrev_b32_e32 v78, 16, v132
	v_and_b32_e32 v79, 0xffff0000, v132
	v_lshlrev_b32_e32 v80, 16, v133
	v_and_b32_e32 v81, 0xffff0000, v133
	v_lshlrev_b32_e32 v86, 16, v135
	v_and_b32_e32 v87, 0xffff0000, v135
	v_pk_fma_f32 v[74:75], v[74:75], v[84:85], v[80:81] op_sel_hi:[1,0,1]
	v_pk_fma_f32 v[72:73], v[72:73], v[84:85], v[78:79] op_sel_hi:[1,0,1]
	v_pk_fma_f32 v[78:79], v[70:71], v[84:85], v[86:87] op_sel_hi:[1,0,1]
	v_pk_fma_f32 v[70:71], v[68:69], v[84:85], v[82:83] op_sel_hi:[1,0,1]
	v_mul_f32_e32 v68, v73, v73
	v_mul_f32_e32 v69, v75, v75
	v_fmac_f32_e32 v68, v72, v72
	v_fmac_f32_e32 v69, v74, v74
	v_add_f32_e32 v68, v68, v69
	v_mul_f32_e32 v69, v71, v71
	v_mul_f32_e32 v80, v79, v79
	v_fmac_f32_e32 v69, v70, v70
	v_fmac_f32_e32 v80, v78, v78
	v_add_f32_e32 v69, v69, v80
	v_add_f32_e32 v68, v68, v69
	v_add_f32_e32 v80, v85, v68
	v_cvt_pk_bf16_f32 v68, v72, v73
	v_cvt_pk_bf16_f32 v69, v74, v75
	v_cvt_pk_bf16_f32 v70, v70, v71
	v_cvt_pk_bf16_f32 v71, v78, v79
	global_store_dwordx4 v[76:77], v[68:71], off offset:256
	ds_bpermute_b32 v68, v3, v80
	s_waitcnt lgkmcnt(0)
	v_add_f32_e32 v68, v80, v68
	ds_bpermute_b32 v69, v117, v68
	s_and_saveexec_b64 s[2:3], s[40:41]
	s_cbranch_execz .LBB0_939
	s_waitcnt lgkmcnt(0)
	v_add_f32_e32 v70, v68, v69
	v_floor_f32_e32 v72, v70
	v_sub_f32_e32 v70, v70, v72
	v_mul_f32_e32 v70, 0x4f800000, v70
	v_cvt_u32_f32_e32 v71, v72
	v_cvt_u32_f32_e32 v70, v70
	v_lshl_add_u64 v[68:69], v[186:187], 3, s[4:5]
	global_atomic_add_x2 v[68:69], v[70:71], off
.LBB0_939:
	s_or_b64 exec, exec, s[2:3]
	v_add_u32_e32 v102, 0x80, v182
	v_ashrrev_i32_e32 v103, 31, v102
	v_lshlrev_b64 v[110:111], 12, v[102:103]
	v_add_u32_e32 v100, 0x90, v182
	s_waitcnt lgkmcnt(0)
	v_lshl_add_u64 v[68:69], v[184:185], 0, v[110:111]
	v_ashrrev_i32_e32 v101, 31, v100
	global_load_dwordx4 v[106:109], v[68:69], off
	global_load_dwordx4 v[92:95], v[68:69], off offset:256
	v_lshlrev_b64 v[68:69], 12, v[100:101]
	v_add_u32_e32 v98, 0xa0, v182
	v_lshl_add_u64 v[68:69], v[184:185], 0, v[68:69]
	v_ashrrev_i32_e32 v99, 31, v98
	global_load_dwordx4 v[88:91], v[68:69], off
	global_load_dwordx4 v[84:87], v[68:69], off offset:256
	v_lshlrev_b64 v[68:69], 12, v[98:99]
	v_add_u32_e32 v96, 0xb0, v182
	v_lshl_add_u64 v[68:69], v[184:185], 0, v[68:69]
	v_ashrrev_i32_e32 v97, 31, v96
	global_load_dwordx4 v[80:83], v[68:69], off
	global_load_dwordx4 v[76:79], v[68:69], off offset:256
	v_lshlrev_b64 v[68:69], 12, v[96:97]
	v_lshl_add_u64 v[68:69], v[184:185], 0, v[68:69]
	global_load_dwordx4 v[72:75], v[68:69], off
	s_nop 0
	global_load_dwordx4 v[68:71], v[68:69], off offset:256
	s_nop 1
	v_mov_b32_e32 v104, v228
	v_mov_b32_e32 v105, v229
	v_mov_b32_e32 v113, v2
	s_waitcnt vmcnt(0)
; __device__ __forceinline__ void ss_add(ss_t* p, float sq) { const float fl = floorf(sq); const unsigned hi = (unsigned)fl, lo = (unsigned)((sq - fl) * 4294967296.0f); atomicAdd(p, ((ss_t)hi << 32) | (ss_t)lo); }
; __device__ __forceinline__ float ss_get(const ss_t* p) { const ss_t v = *p; return (float)(unsigned)(v >> 32) + (float)(unsigned)v * 2.3283064365386963e-10f; }
; __device__ __forceinline__ unsigned pkbf(float lo, float hi) { typedef float f2_t __attribute__((ext_vector_type(2))); typedef __bf16 b2_t __attribute__((ext_vector_type(2))); f2_t v = {lo, hi}; b2_t b = __builtin_convertvector(v, b2_t); return __builtin_bit_cast(unsigned, b); }
;     __device__ __forceinline__ void operator()(const f32x4 (&acc)[2][2][4][2], const Unit& u, int wr, int wc, int fr, int fq) const {
;     ...
;             for (int m = 0; m < 4; ++m) { const int row = row0 + ai * HALF + m * 16; const size_t off = (size_t)row * ldc + col0;
;                 float rs = 1.0f; if (KS) rs = 1.0f / sqrtf(ss_get(ssb + row) * (1.0f / 1024.f) + 1e-6f);
;                 float sq = 0.f;
; #pragma unroll
;                 for (int bj = 0; bj < 2; ++bj) { const u32x4 r = res[m][bj];
;                     const f32x4 x0 = (f32x4){__uint_as_float(r.x << 16), __uint_as_float(r.x & 0xffff0000u), __uint_as_float(r.y << 16), __uint_as_float(r.y & 0xffff0000u)};
;                     const f32x4 x1 = (f32x4){__uint_as_float(r.z << 16), __uint_as_float(r.z & 0xffff0000u), __uint_as_float(r.w << 16), __uint_as_float(r.w & 0xffff0000u)};
;                     const f32x4 v0 = x0 + acc[ai][bj][m][0] * rs, v1 = x1 + acc[ai][bj][m][1] * rs;
;                     if (OUT) { *(f32x4*)(OUT + off + bj * HALF) = v0; *(f32x4*)(OUT + off + bj * HALF + 4) = v1; }
;                     else { sq += ((v0[0] * v0[0] + v0[1] * v0[1]) + (v0[2] * v0[2] + v0[3] * v0[3])) + ((v1[0] * v1[0] + v1[1] * v1[1]) + (v1[2] * v1[2] + v1[3] * v1[3]));
;                         u32x4 w; w.x = pkbf(v0[0], v0[1]); w.y = pkbf(v0[2], v0[3]); w.z = pkbf(v1[0], v1[1]); w.w = pkbf(v1[2], v1[3]); *(u32x4*)(XB + off + bj * HALF) = w; } }
;                 if (!OUT) { sq += __shfl_xor(sq, 16); sq += __shfl_xor(sq, 32); if (fq == 0) ss_add(ssq_out + row, sq); } }
	v_mov_b32_e32 v112, v105
	v_lshlrev_b64 v[112:113], s43, v[112:113]
	v_min_u32_e32 v105, 1, v112
	v_or_b32_e32 v105, v113, v105
	v_cvt_f32_u32_e32 v105, v105
	v_cvt_f32_u32_e32 v104, v104
	v_ldexp_f32 v105, v105, s46
	v_fmac_f32_e32 v105, 0x2f800000, v104
	v_fmamk_f32 v104, v105, 0x3a800000, v205
	v_cmp_gt_f32_e32 vcc, s97, v104
	v_mul_f32_e32 v105, 0x4f800000, v104
	s_nop 0
	v_cndmask_b32_e32 v104, v104, v105, vcc
	v_sqrt_f32_e32 v105, v104
	s_nop 0
	v_add_u32_e32 v112, -1, v105
	v_fma_f32 v113, -v112, v105, v104
	v_cmp_ge_f32_e64 s[2:3], 0, v113
	v_add_u32_e32 v113, 1, v105
	s_nop 0
	v_cndmask_b32_e64 v112, v105, v112, s[2:3]
	v_fma_f32 v105, -v113, v105, v104
	v_cmp_lt_f32_e64 s[2:3], 0, v105
	s_nop 1
	v_cndmask_b32_e64 v105, v112, v113, s[2:3]
	v_mul_f32_e32 v112, 0x37800000, v105
	v_cndmask_b32_e32 v105, v105, v112, vcc
	v_cmp_class_f32_e32 vcc, v104, v206
	s_nop 1
	v_cndmask_b32_e32 v104, v105, v104, vcc
	v_div_scale_f32 v105, s[2:3], v104, v104, 1.0
	v_rcp_f32_e32 v112, v105
	s_nop 0
	v_fma_f32 v113, -v105, v112, 1.0
	v_fmac_f32_e32 v112, v113, v112
	v_div_scale_f32 v113, vcc, 1.0, v104, 1.0
	v_mul_f32_e32 v114, v113, v112
	v_fma_f32 v115, -v105, v114, v113
	v_fmac_f32_e32 v114, v115, v112
	v_fma_f32 v105, -v105, v114, v113
	v_div_fmas_f32 v105, v105, v112, v114
	v_div_fixup_f32 v104, v105, v104, 1.0
	v_lshlrev_b32_e32 v112, 16, v106
	v_and_b32_e32 v113, 0xffff0000, v106
	v_lshlrev_b32_e32 v106, 16, v107
	v_and_b32_e32 v107, 0xffff0000, v107
	v_lshlrev_b32_e32 v114, 16, v108
	v_and_b32_e32 v115, 0xffff0000, v108
	v_lshlrev_b32_e32 v108, 16, v109
	v_and_b32_e32 v109, 0xffff0000, v109
	v_pk_fma_f32 v[66:67], v[66:67], v[104:105], v[106:107] op_sel_hi:[1,0,1]
	v_pk_fma_f32 v[64:65], v[64:65], v[104:105], v[112:113] op_sel_hi:[1,0,1]
	v_pk_fma_f32 v[106:107], v[62:63], v[104:105], v[108:109] op_sel_hi:[1,0,1]
	v_mul_f32_e32 v62, v65, v65
	v_mul_f32_e32 v63, v67, v67
	v_pk_fma_f32 v[60:61], v[60:61], v[104:105], v[114:115] op_sel_hi:[1,0,1]
	v_fmac_f32_e32 v62, v64, v64
	v_fmac_f32_e32 v63, v66, v66
	v_add_f32_e32 v62, v62, v63
	v_mul_f32_e32 v63, v61, v61
	v_mul_f32_e32 v105, v107, v107
	v_fmac_f32_e32 v63, v60, v60
	v_fmac_f32_e32 v105, v106, v106
	v_add_f32_e32 v63, v63, v105
	v_add_f32_e32 v105, v62, v63
	v_cvt_pk_bf16_f32 v62, v64, v65
	v_cvt_pk_bf16_f32 v64, v60, v61
	v_lshl_add_u64 v[60:61], s[64:65], 0, v[110:111]
	v_cvt_pk_bf16_f32 v63, v66, v67
	v_cvt_pk_bf16_f32 v65, v106, v107
	v_lshl_add_u64 v[60:61], v[0:1], 1, v[60:61]
	global_store_dwordx4 v[60:61], v[62:65], off
	v_lshlrev_b32_e32 v66, 16, v94
	v_and_b32_e32 v67, 0xffff0000, v94
	v_lshlrev_b32_e32 v62, 16, v92
	v_and_b32_e32 v63, 0xffff0000, v92
	v_lshlrev_b32_e32 v64, 16, v93
	v_and_b32_e32 v65, 0xffff0000, v93
	v_lshlrev_b32_e32 v92, 16, v95
	v_and_b32_e32 v93, 0xffff0000, v95
	v_pk_fma_f32 v[58:59], v[58:59], v[104:105], v[64:65] op_sel_hi:[1,0,1]
	v_pk_fma_f32 v[56:57], v[56:57], v[104:105], v[62:63] op_sel_hi:[1,0,1]
	v_pk_fma_f32 v[62:63], v[54:55], v[104:105], v[92:93] op_sel_hi:[1,0,1]
	v_pk_fma_f32 v[54:55], v[52:53], v[104:105], v[66:67] op_sel_hi:[1,0,1]
	v_mul_f32_e32 v52, v57, v57
	v_mul_f32_e32 v53, v59, v59
	v_fmac_f32_e32 v52, v56, v56
	v_fmac_f32_e32 v53, v58, v58
	v_add_f32_e32 v52, v52, v53
	v_mul_f32_e32 v53, v55, v55
	v_mul_f32_e32 v64, v63, v63
	v_fmac_f32_e32 v53, v54, v54
	v_fmac_f32_e32 v64, v62, v62
	v_add_f32_e32 v53, v53, v64
	v_add_f32_e32 v52, v52, v53
	v_add_f32_e32 v64, v105, v52
	v_cvt_pk_bf16_f32 v52, v56, v57
	v_cvt_pk_bf16_f32 v53, v58, v59
	v_cvt_pk_bf16_f32 v54, v54, v55
	v_cvt_pk_bf16_f32 v55, v62, v63
	global_store_dwordx4 v[60:61], v[52:55], off offset:256
	ds_bpermute_b32 v52, v3, v64
	s_waitcnt lgkmcnt(0)
	v_add_f32_e32 v52, v64, v52
	ds_bpermute_b32 v53, v117, v52
	s_and_saveexec_b64 s[2:3], s[40:41]
	s_cbranch_execz .LBB0_941
	s_waitcnt lgkmcnt(0)
	v_add_f32_e32 v54, v52, v53
	v_floor_f32_e32 v56, v54
	v_sub_f32_e32 v54, v54, v56
	v_mul_f32_e32 v54, 0x4f800000, v54
	v_cvt_u32_f32_e32 v55, v56
	v_cvt_u32_f32_e32 v54, v54
	v_lshl_add_u64 v[52:53], v[102:103], 3, s[4:5]
	global_atomic_add_x2 v[52:53], v[54:55], off
.LBB0_941:
	s_or_b64 exec, exec, s[2:3]
	s_waitcnt lgkmcnt(0)
	s_nop 1
	v_mov_b32_e32 v52, v230
	v_mov_b32_e32 v53, v231
	v_mov_b32_e32 v57, v2
	v_lshlrev_b32_e32 v62, 16, v91
	v_and_b32_e32 v63, 0xffff0000, v91
	v_lshlrev_b32_e32 v60, 16, v90
	v_and_b32_e32 v61, 0xffff0000, v90
	v_lshlrev_b64 v[54:55], 11, v[100:101]
	v_mov_b32_e32 v56, v53
	v_lshlrev_b64 v[56:57], s43, v[56:57]
	v_min_u32_e32 v53, 1, v56
	v_or_b32_e32 v53, v57, v53
	v_cvt_f32_u32_e32 v53, v53
	v_cvt_f32_u32_e32 v52, v52
	v_ldexp_f32 v53, v53, s46
	v_fmac_f32_e32 v53, 0x2f800000, v52
	v_fmamk_f32 v52, v53, 0x3a800000, v205
	v_cmp_gt_f32_e32 vcc, s97, v52
	v_mul_f32_e32 v53, 0x4f800000, v52
	s_nop 0
	v_cndmask_b32_e32 v52, v52, v53, vcc
	v_sqrt_f32_e32 v53, v52
	s_nop 0
	v_add_u32_e32 v56, -1, v53
	v_fma_f32 v57, -v56, v53, v52
	v_cmp_ge_f32_e64 s[2:3], 0, v57
	v_add_u32_e32 v57, 1, v53
	s_nop 0
	v_cndmask_b32_e64 v56, v53, v56, s[2:3]
	v_fma_f32 v53, -v57, v53, v52
	v_cmp_lt_f32_e64 s[2:3], 0, v53
	s_nop 1
	v_cndmask_b32_e64 v53, v56, v57, s[2:3]
	v_mul_f32_e32 v56, 0x37800000, v53
	v_cndmask_b32_e32 v53, v53, v56, vcc
	v_cmp_class_f32_e32 vcc, v52, v206
	s_nop 1
	v_cndmask_b32_e32 v52, v53, v52, vcc
	v_div_scale_f32 v53, s[2:3], v52, v52, 1.0
	v_rcp_f32_e32 v56, v53
	s_nop 0
	v_fma_f32 v57, -v53, v56, 1.0
	v_fmac_f32_e32 v56, v57, v56
	v_div_scale_f32 v57, vcc, 1.0, v52, 1.0
	v_mul_f32_e32 v58, v57, v56
	v_fma_f32 v59, -v53, v58, v57
	v_fmac_f32_e32 v58, v59, v56
	v_fma_f32 v53, -v53, v58, v57
	v_div_fmas_f32 v53, v53, v56, v58
; __device__ __forceinline__ void ss_add(ss_t* p, float sq) { const float fl = floorf(sq); const unsigned hi = (unsigned)fl, lo = (unsigned)((sq - fl) * 4294967296.0f); atomicAdd(p, ((ss_t)hi << 32) | (ss_t)lo); }
; __device__ __forceinline__ float ss_get(const ss_t* p) { const ss_t v = *p; return (float)(unsigned)(v >> 32) + (float)(unsigned)v * 2.3283064365386963e-10f; }
; __device__ __forceinline__ unsigned pkbf(float lo, float hi) { typedef float f2_t __attribute__((ext_vector_type(2))); typedef __bf16 b2_t __attribute__((ext_vector_type(2))); f2_t v = {lo, hi}; b2_t b = __builtin_convertvector(v, b2_t); return __builtin_bit_cast(unsigned, b); }
;     __device__ __forceinline__ void operator()(const f32x4 (&acc)[2][2][4][2], const Unit& u, int wr, int wc, int fr, int fq) const {
;     ...
;             for (int m = 0; m < 4; ++m) { const int row = row0 + ai * HALF + m * 16; const size_t off = (size_t)row * ldc + col0;
;                 float rs = 1.0f; if (KS) rs = 1.0f / sqrtf(ss_get(ssb + row) * (1.0f / 1024.f) + 1e-6f);
;                 float sq = 0.f;
; #pragma unroll
;                 for (int bj = 0; bj < 2; ++bj) { const u32x4 r = res[m][bj];
;                     const f32x4 x0 = (f32x4){__uint_as_float(r.x << 16), __uint_as_float(r.x & 0xffff0000u), __uint_as_float(r.y << 16), __uint_as_float(r.y & 0xffff0000u)};
;                     const f32x4 x1 = (f32x4){__uint_as_float(r.z << 16), __uint_as_float(r.z & 0xffff0000u), __uint_as_float(r.w << 16), __uint_as_float(r.w & 0xffff0000u)};
;                     const f32x4 v0 = x0 + acc[ai][bj][m][0] * rs, v1 = x1 + acc[ai][bj][m][1] * rs;
;                     if (OUT) { *(f32x4*)(OUT + off + bj * HALF) = v0; *(f32x4*)(OUT + off + bj * HALF + 4) = v1; }
;                     else { sq += ((v0[0] * v0[0] + v0[1] * v0[1]) + (v0[2] * v0[2] + v0[3] * v0[3])) + ((v1[0] * v1[0] + v1[1] * v1[1]) + (v1[2] * v1[2] + v1[3] * v1[3]));
;                         u32x4 w; w.x = pkbf(v0[0], v0[1]); w.y = pkbf(v0[2], v0[3]); w.z = pkbf(v1[0], v1[1]); w.w = pkbf(v1[2], v1[3]); *(u32x4*)(XB + off + bj * HALF) = w; } }
;                 if (!OUT) { sq += __shfl_xor(sq, 16); sq += __shfl_xor(sq, 32); if (fq == 0) ss_add(ssq_out + row, sq); } }
	v_div_fixup_f32 v52, v53, v52, 1.0
	v_lshlrev_b32_e32 v56, 16, v88
	v_and_b32_e32 v57, 0xffff0000, v88
	v_lshlrev_b32_e32 v58, 16, v89
	v_and_b32_e32 v59, 0xffff0000, v89
	v_pk_fma_f32 v[50:51], v[50:51], v[52:53], v[58:59] op_sel_hi:[1,0,1]
	v_pk_fma_f32 v[48:49], v[48:49], v[52:53], v[56:57] op_sel_hi:[1,0,1]
	v_pk_fma_f32 v[56:57], v[46:47], v[52:53], v[62:63] op_sel_hi:[1,0,1]
	v_mul_f32_e32 v46, v49, v49
	v_mul_f32_e32 v47, v51, v51
	v_pk_fma_f32 v[44:45], v[44:45], v[52:53], v[60:61] op_sel_hi:[1,0,1]
	v_fmac_f32_e32 v46, v48, v48
	v_fmac_f32_e32 v47, v50, v50
	v_add_f32_e32 v46, v46, v47
	v_mul_f32_e32 v47, v45, v45
	v_mul_f32_e32 v53, v57, v57
	v_fmac_f32_e32 v47, v44, v44
	v_fmac_f32_e32 v53, v56, v56
	v_add_f32_e32 v47, v47, v53
	v_add_f32_e32 v53, v46, v47
	v_cvt_pk_bf16_f32 v46, v48, v49
	v_cvt_pk_bf16_f32 v48, v44, v45
	v_lshl_add_u64 v[44:45], v[54:55], 1, s[64:65]
	v_cvt_pk_bf16_f32 v47, v50, v51
	v_cvt_pk_bf16_f32 v49, v56, v57
	v_lshl_add_u64 v[44:45], v[0:1], 1, v[44:45]
	global_store_dwordx4 v[44:45], v[46:49], off
	v_lshlrev_b32_e32 v50, 16, v86
	v_and_b32_e32 v51, 0xffff0000, v86
	v_lshlrev_b32_e32 v46, 16, v84
	v_and_b32_e32 v47, 0xffff0000, v84
	v_lshlrev_b32_e32 v48, 16, v85
	v_and_b32_e32 v49, 0xffff0000, v85
	v_lshlrev_b32_e32 v54, 16, v87
	v_and_b32_e32 v55, 0xffff0000, v87
	v_pk_fma_f32 v[42:43], v[42:43], v[52:53], v[48:49] op_sel_hi:[1,0,1]
	v_pk_fma_f32 v[40:41], v[40:41], v[52:53], v[46:47] op_sel_hi:[1,0,1]
	v_pk_fma_f32 v[46:47], v[38:39], v[52:53], v[54:55] op_sel_hi:[1,0,1]
	v_pk_fma_f32 v[38:39], v[36:37], v[52:53], v[50:51] op_sel_hi:[1,0,1]
	v_mul_f32_e32 v36, v41, v41
	v_mul_f32_e32 v37, v43, v43
	v_fmac_f32_e32 v36, v40, v40
	v_fmac_f32_e32 v37, v42, v42
	v_add_f32_e32 v36, v36, v37
	v_mul_f32_e32 v37, v39, v39
	v_mul_f32_e32 v48, v47, v47
	v_fmac_f32_e32 v37, v38, v38
	v_fmac_f32_e32 v48, v46, v46
	v_add_f32_e32 v37, v37, v48
	v_add_f32_e32 v36, v36, v37
	v_add_f32_e32 v48, v53, v36
	v_cvt_pk_bf16_f32 v36, v40, v41
	v_cvt_pk_bf16_f32 v37, v42, v43
	v_cvt_pk_bf16_f32 v38, v38, v39
	v_cvt_pk_bf16_f32 v39, v46, v47
	global_store_dwordx4 v[44:45], v[36:39], off offset:256
	ds_bpermute_b32 v36, v3, v48
	s_waitcnt lgkmcnt(0)
	v_add_f32_e32 v36, v48, v36
	ds_bpermute_b32 v37, v117, v36
	s_and_saveexec_b64 s[2:3], s[40:41]
	s_cbranch_execz .LBB0_943
	s_waitcnt lgkmcnt(0)
	v_add_f32_e32 v38, v36, v37
	v_floor_f32_e32 v40, v38
	v_sub_f32_e32 v38, v38, v40
	v_mul_f32_e32 v38, 0x4f800000, v38
	v_cvt_u32_f32_e32 v39, v40
	v_cvt_u32_f32_e32 v38, v38
	v_lshl_add_u64 v[36:37], v[100:101], 3, s[4:5]
	global_atomic_add_x2 v[36:37], v[38:39], off
.LBB0_943:
	s_or_b64 exec, exec, s[2:3]
	s_waitcnt lgkmcnt(0)
	s_nop 1
	v_mov_b32_e32 v36, v232
	v_mov_b32_e32 v37, v233
	v_mov_b32_e32 v41, v2
	v_lshlrev_b32_e32 v46, 16, v83
	v_and_b32_e32 v47, 0xffff0000, v83
	v_lshlrev_b32_e32 v44, 16, v82
	v_and_b32_e32 v45, 0xffff0000, v82
	v_lshlrev_b64 v[38:39], 11, v[98:99]
	v_mov_b32_e32 v40, v37
	v_lshlrev_b64 v[40:41], s43, v[40:41]
	v_min_u32_e32 v37, 1, v40
	v_or_b32_e32 v37, v41, v37
	v_cvt_f32_u32_e32 v37, v37
	v_cvt_f32_u32_e32 v36, v36
	v_ldexp_f32 v37, v37, s46
	v_fmac_f32_e32 v37, 0x2f800000, v36
	v_fmamk_f32 v36, v37, 0x3a800000, v205
	v_cmp_gt_f32_e32 vcc, s97, v36
	v_mul_f32_e32 v37, 0x4f800000, v36
	s_nop 0
	v_cndmask_b32_e32 v36, v36, v37, vcc
	v_sqrt_f32_e32 v37, v36
	s_nop 0
	v_add_u32_e32 v40, -1, v37
	v_fma_f32 v41, -v40, v37, v36
	v_cmp_ge_f32_e64 s[2:3], 0, v41
	v_add_u32_e32 v41, 1, v37
	s_nop 0
	v_cndmask_b32_e64 v40, v37, v40, s[2:3]
	v_fma_f32 v37, -v41, v37, v36
	v_cmp_lt_f32_e64 s[2:3], 0, v37
	s_nop 1
	v_cndmask_b32_e64 v37, v40, v41, s[2:3]
	v_mul_f32_e32 v40, 0x37800000, v37
	v_cndmask_b32_e32 v37, v37, v40, vcc
	v_cmp_class_f32_e32 vcc, v36, v206
	s_nop 1
	v_cndmask_b32_e32 v36, v37, v36, vcc
	v_div_scale_f32 v37, s[2:3], v36, v36, 1.0
	v_rcp_f32_e32 v40, v37
	s_nop 0
	v_fma_f32 v41, -v37, v40, 1.0
	v_fmac_f32_e32 v40, v41, v40
	v_div_scale_f32 v41, vcc, 1.0, v36, 1.0
	v_mul_f32_e32 v42, v41, v40
	v_fma_f32 v43, -v37, v42, v41
	v_fmac_f32_e32 v42, v43, v40
	v_fma_f32 v37, -v37, v42, v41
	v_div_fmas_f32 v37, v37, v40, v42
	v_div_fixup_f32 v36, v37, v36, 1.0
	v_lshlrev_b32_e32 v40, 16, v80
	v_and_b32_e32 v41, 0xffff0000, v80
	v_lshlrev_b32_e32 v42, 16, v81
	v_and_b32_e32 v43, 0xffff0000, v81
	v_pk_fma_f32 v[34:35], v[34:35], v[36:37], v[42:43] op_sel_hi:[1,0,1]
	v_pk_fma_f32 v[32:33], v[32:33], v[36:37], v[40:41] op_sel_hi:[1,0,1]
	v_pk_fma_f32 v[40:41], v[30:31], v[36:37], v[46:47] op_sel_hi:[1,0,1]
	v_mul_f32_e32 v30, v33, v33
	v_mul_f32_e32 v31, v35, v35
	v_pk_fma_f32 v[28:29], v[28:29], v[36:37], v[44:45] op_sel_hi:[1,0,1]
	v_fmac_f32_e32 v30, v32, v32
	v_fmac_f32_e32 v31, v34, v34
	v_add_f32_e32 v30, v30, v31
	v_mul_f32_e32 v31, v29, v29
	v_mul_f32_e32 v37, v41, v41
	v_fmac_f32_e32 v31, v28, v28
	v_fmac_f32_e32 v37, v40, v40
	v_add_f32_e32 v31, v31, v37
	v_add_f32_e32 v37, v30, v31
	v_cvt_pk_bf16_f32 v30, v32, v33
	v_cvt_pk_bf16_f32 v32, v28, v29
	v_lshl_add_u64 v[28:29], v[38:39], 1, s[64:65]
	v_cvt_pk_bf16_f32 v31, v34, v35
	v_cvt_pk_bf16_f32 v33, v40, v41
	v_lshl_add_u64 v[28:29], v[0:1], 1, v[28:29]
	global_store_dwordx4 v[28:29], v[30:33], off
	v_lshlrev_b32_e32 v34, 16, v78
	v_and_b32_e32 v35, 0xffff0000, v78
	v_lshlrev_b32_e32 v30, 16, v76
	v_and_b32_e32 v31, 0xffff0000, v76
	v_lshlrev_b32_e32 v32, 16, v77
	v_and_b32_e32 v33, 0xffff0000, v77
	v_lshlrev_b32_e32 v38, 16, v79
	v_and_b32_e32 v39, 0xffff0000, v79
	v_pk_fma_f32 v[26:27], v[26:27], v[36:37], v[32:33] op_sel_hi:[1,0,1]
	v_pk_fma_f32 v[24:25], v[24:25], v[36:37], v[30:31] op_sel_hi:[1,0,1]
	v_pk_fma_f32 v[30:31], v[22:23], v[36:37], v[38:39] op_sel_hi:[1,0,1]
	v_pk_fma_f32 v[22:23], v[20:21], v[36:37], v[34:35] op_sel_hi:[1,0,1]
	v_mul_f32_e32 v20, v25, v25
	v_mul_f32_e32 v21, v27, v27
	v_fmac_f32_e32 v20, v24, v24
	v_fmac_f32_e32 v21, v26, v26
	v_add_f32_e32 v20, v20, v21
	v_mul_f32_e32 v21, v23, v23
	v_mul_f32_e32 v32, v31, v31
	v_fmac_f32_e32 v21, v22, v22
	v_fmac_f32_e32 v32, v30, v30
	v_add_f32_e32 v21, v21, v32
	v_add_f32_e32 v20, v20, v21
	v_add_f32_e32 v32, v37, v20
	v_cvt_pk_bf16_f32 v20, v24, v25
	v_cvt_pk_bf16_f32 v21, v26, v27
	v_cvt_pk_bf16_f32 v22, v22, v23
	v_cvt_pk_bf16_f32 v23, v30, v31
	global_store_dwordx4 v[28:29], v[20:23], off offset:256
	ds_bpermute_b32 v20, v3, v32
	s_waitcnt lgkmcnt(0)
	v_add_f32_e32 v20, v32, v20
	ds_bpermute_b32 v21, v117, v20
	s_and_saveexec_b64 s[2:3], s[40:41]
	s_cbranch_execz .LBB0_945
	s_waitcnt lgkmcnt(0)
	v_add_f32_e32 v22, v20, v21
	v_floor_f32_e32 v24, v22
	v_sub_f32_e32 v22, v22, v24
	v_mul_f32_e32 v22, 0x4f800000, v22
	v_cvt_u32_f32_e32 v23, v24
	v_cvt_u32_f32_e32 v22, v22
	v_lshl_add_u64 v[20:21], v[98:99], 3, s[4:5]
	global_atomic_add_x2 v[20:21], v[22:23], off
; __device__ __forceinline__ void ss_add(ss_t* p, float sq) { const float fl = floorf(sq); const unsigned hi = (unsigned)fl, lo = (unsigned)((sq - fl) * 4294967296.0f); atomicAdd(p, ((ss_t)hi << 32) | (ss_t)lo); }
; __device__ __forceinline__ float ss_get(const ss_t* p) { const ss_t v = *p; return (float)(unsigned)(v >> 32) + (float)(unsigned)v * 2.3283064365386963e-10f; }
; __device__ __forceinline__ unsigned pkbf(float lo, float hi) { typedef float f2_t __attribute__((ext_vector_type(2))); typedef __bf16 b2_t __attribute__((ext_vector_type(2))); f2_t v = {lo, hi}; b2_t b = __builtin_convertvector(v, b2_t); return __builtin_bit_cast(unsigned, b); }
;     __device__ __forceinline__ void operator()(const f32x4 (&acc)[2][2][4][2], const Unit& u, int wr, int wc, int fr, int fq) const {
;     ...
;             for (int m = 0; m < 4; ++m) { const int row = row0 + ai * HALF + m * 16; const size_t off = (size_t)row * ldc + col0;
;                 float rs = 1.0f; if (KS) rs = 1.0f / sqrtf(ss_get(ssb + row) * (1.0f / 1024.f) + 1e-6f);
;                 float sq = 0.f;
; #pragma unroll
;                 for (int bj = 0; bj < 2; ++bj) { const u32x4 r = res[m][bj];
;                     const f32x4 x0 = (f32x4){__uint_as_float(r.x << 16), __uint_as_float(r.x & 0xffff0000u), __uint_as_float(r.y << 16), __uint_as_float(r.y & 0xffff0000u)};
;                     const f32x4 x1 = (f32x4){__uint_as_float(r.z << 16), __uint_as_float(r.z & 0xffff0000u), __uint_as_float(r.w << 16), __uint_as_float(r.w & 0xffff0000u)};
;                     const f32x4 v0 = x0 + acc[ai][bj][m][0] * rs, v1 = x1 + acc[ai][bj][m][1] * rs;
;                     if (OUT) { *(f32x4*)(OUT + off + bj * HALF) = v0; *(f32x4*)(OUT + off + bj * HALF + 4) = v1; }
;                     else { sq += ((v0[0] * v0[0] + v0[1] * v0[1]) + (v0[2] * v0[2] + v0[3] * v0[3])) + ((v1[0] * v1[0] + v1[1] * v1[1]) + (v1[2] * v1[2] + v1[3] * v1[3]));
;                         u32x4 w; w.x = pkbf(v0[0], v0[1]); w.y = pkbf(v0[2], v0[3]); w.z = pkbf(v1[0], v1[1]); w.w = pkbf(v1[2], v1[3]); *(u32x4*)(XB + off + bj * HALF) = w; } }
;                 if (!OUT) { sq += __shfl_xor(sq, 16); sq += __shfl_xor(sq, 32); if (fq == 0) ss_add(ssq_out + row, sq); } }
.LBB0_945:
	s_or_b64 exec, exec, s[2:3]
	s_waitcnt lgkmcnt(0)
	s_nop 1
	v_mov_b32_e32 v20, v234
	v_mov_b32_e32 v21, v235
	v_mov_b32_e32 v25, v2
	v_lshlrev_b32_e32 v28, 16, v74
	v_and_b32_e32 v29, 0xffff0000, v74
	v_lshlrev_b32_e32 v30, 16, v75
	v_and_b32_e32 v31, 0xffff0000, v75
	v_lshlrev_b64 v[22:23], 11, v[96:97]
	v_mov_b32_e32 v24, v21
	v_lshlrev_b64 v[24:25], s43, v[24:25]
	v_min_u32_e32 v21, 1, v24
	v_or_b32_e32 v21, v25, v21
	v_cvt_f32_u32_e32 v21, v21
	v_cvt_f32_u32_e32 v20, v20
	v_ldexp_f32 v21, v21, s46
	v_fmac_f32_e32 v21, 0x2f800000, v20
	v_fmamk_f32 v20, v21, 0x3a800000, v205
	v_cmp_gt_f32_e32 vcc, s97, v20
	v_mul_f32_e32 v21, 0x4f800000, v20
	s_nop 0
	v_cndmask_b32_e32 v20, v20, v21, vcc
	v_sqrt_f32_e32 v21, v20
	s_nop 0
	v_add_u32_e32 v24, -1, v21
	v_fma_f32 v25, -v24, v21, v20
	v_cmp_ge_f32_e64 s[2:3], 0, v25
	v_add_u32_e32 v25, 1, v21
	s_nop 0
	v_cndmask_b32_e64 v24, v21, v24, s[2:3]
	v_fma_f32 v21, -v25, v21, v20
	v_cmp_lt_f32_e64 s[2:3], 0, v21
	s_nop 1
	v_cndmask_b32_e64 v21, v24, v25, s[2:3]
	v_mul_f32_e32 v24, 0x37800000, v21
	v_cndmask_b32_e32 v21, v21, v24, vcc
	v_cmp_class_f32_e32 vcc, v20, v206
	s_nop 1
	v_cndmask_b32_e32 v20, v21, v20, vcc
	v_div_scale_f32 v21, s[2:3], v20, v20, 1.0
	v_rcp_f32_e32 v24, v21
	s_nop 0
	v_fma_f32 v25, -v21, v24, 1.0
	v_fmac_f32_e32 v24, v25, v24
	v_div_scale_f32 v25, vcc, 1.0, v20, 1.0
	v_mul_f32_e32 v26, v25, v24
	v_fma_f32 v27, -v21, v26, v25
	v_fmac_f32_e32 v26, v27, v24
	v_fma_f32 v21, -v21, v26, v25
	v_div_fmas_f32 v21, v21, v24, v26
	v_div_fixup_f32 v20, v21, v20, 1.0
	v_lshlrev_b32_e32 v24, 16, v72
	v_and_b32_e32 v25, 0xffff0000, v72
	v_lshlrev_b32_e32 v26, 16, v73
	v_and_b32_e32 v27, 0xffff0000, v73
	v_pk_fma_f32 v[18:19], v[18:19], v[20:21], v[26:27] op_sel_hi:[1,0,1]
	v_pk_fma_f32 v[16:17], v[16:17], v[20:21], v[24:25] op_sel_hi:[1,0,1]
	v_pk_fma_f32 v[24:25], v[14:15], v[20:21], v[30:31] op_sel_hi:[1,0,1]
	v_pk_fma_f32 v[14:15], v[12:13], v[20:21], v[28:29] op_sel_hi:[1,0,1]
	v_mul_f32_e32 v12, v17, v17
	v_mul_f32_e32 v13, v19, v19
	v_fmac_f32_e32 v12, v16, v16
	v_fmac_f32_e32 v13, v18, v18
	v_add_f32_e32 v12, v12, v13
	v_mul_f32_e32 v13, v15, v15
	v_mul_f32_e32 v21, v25, v25
	v_fmac_f32_e32 v13, v14, v14
	v_fmac_f32_e32 v21, v24, v24
	v_add_f32_e32 v13, v13, v21
	v_add_f32_e32 v21, v12, v13
	v_cvt_pk_bf16_f32 v12, v16, v17
	v_lshl_add_u64 v[16:17], v[22:23], 1, s[64:65]
	v_cvt_pk_bf16_f32 v13, v18, v19
	v_cvt_pk_bf16_f32 v14, v14, v15
	v_cvt_pk_bf16_f32 v15, v24, v25
	v_lshl_add_u64 v[0:1], v[0:1], 1, v[16:17]
	global_store_dwordx4 v[0:1], v[12:15], off
	v_lshlrev_b32_e32 v16, 16, v70
	v_and_b32_e32 v17, 0xffff0000, v70
	v_lshlrev_b32_e32 v12, 16, v68
	v_and_b32_e32 v13, 0xffff0000, v68
	v_lshlrev_b32_e32 v14, 16, v69
	v_and_b32_e32 v15, 0xffff0000, v69
	v_lshlrev_b32_e32 v18, 16, v71
	v_and_b32_e32 v19, 0xffff0000, v71
	v_pk_fma_f32 v[10:11], v[10:11], v[20:21], v[14:15] op_sel_hi:[1,0,1]
	v_pk_fma_f32 v[8:9], v[8:9], v[20:21], v[12:13] op_sel_hi:[1,0,1]
	v_pk_fma_f32 v[12:13], v[6:7], v[20:21], v[18:19] op_sel_hi:[1,0,1]
	v_pk_fma_f32 v[6:7], v[4:5], v[20:21], v[16:17] op_sel_hi:[1,0,1]
	v_mul_f32_e32 v4, v9, v9
	v_mul_f32_e32 v5, v11, v11
	v_fmac_f32_e32 v4, v8, v8
	v_fmac_f32_e32 v5, v10, v10
	v_add_f32_e32 v4, v4, v5
	v_mul_f32_e32 v5, v7, v7
	v_mul_f32_e32 v14, v13, v13
	v_fmac_f32_e32 v5, v6, v6
	v_fmac_f32_e32 v14, v12, v12
	v_add_f32_e32 v5, v5, v14
	v_add_f32_e32 v4, v4, v5
	v_add_f32_e32 v14, v21, v4
	v_cvt_pk_bf16_f32 v4, v8, v9
	v_cvt_pk_bf16_f32 v5, v10, v11
	v_cvt_pk_bf16_f32 v6, v6, v7
	v_cvt_pk_bf16_f32 v7, v12, v13
	global_store_dwordx4 v[0:1], v[4:7], off offset:256
	ds_bpermute_b32 v0, v3, v14
	s_waitcnt lgkmcnt(0)
	v_add_f32_e32 v0, v14, v0
	ds_bpermute_b32 v1, v117, v0
	s_and_saveexec_b64 s[2:3], s[40:41]
	s_cbranch_execz .LBB0_947
	s_waitcnt lgkmcnt(0)
	v_add_f32_e32 v3, v0, v1
	v_floor_f32_e32 v4, v3
	v_sub_f32_e32 v3, v3, v4
	v_mul_f32_e32 v3, 0x4f800000, v3
	v_cvt_u32_f32_e32 v5, v4
	v_cvt_u32_f32_e32 v4, v3
	v_lshl_add_u64 v[0:1], v[96:97], 3, s[4:5]
	global_atomic_add_x2 v[0:1], v[4:5], off
